# stack: deeper V prefetch (diff attn) + saddr LDS-DMA form + epilogue opening waits vmcnt(8) + 64-bit acc zeroing + relaxed first K-tile waits
# speedup vs baseline: 1.0132x; 1.0052x over previous
; #define PG8_STAGE(bufoff, gbase, voff) do { _Pragma("unroll") for (int _i = 0; _i < 2; ++_i) \
;         __builtin_amdgcn_global_load_lds((const unsigned*)((const char*)(gbase) + (voff)[_i]), (PG8_LAS unsigned*)(lds + (bufoff) + ldsw + _i * 8192), 16, 0, 0); } while (0)
; #define PG8_LDA(dst, b, h) do { _Pragma("unroll") for (int m = 0; m < 4; ++m) _Pragma("unroll") for (int k = 0; k < 2; ++k) dst[m][k] = *(const PG8_LAS bf16x8*)(lds + PG8_SA(b, h) + aoff + m * 2048 + k * 1024); } while (0)
; #define PG8_WAIT_V(n) asm volatile("s_waitcnt vmcnt(" #n ")" ::: "memory")
; #define PG8_BAR __builtin_amdgcn_s_barrier()
; template <class Epi, class Sched, bool ALIGN_EPI = false, bool SP2 = false>
; __device__ __forceinline__ void gemm_phase(PG8_LAS unsigned char* lds, const Gemm g, const Sched& S, const Epi& E, const int tid_in) {
;     ...
;         float rsv[8]; E.pre(cur, wr, fr, rsv);
;         const bool has_next = S.next(ui + 1, nxt);
;         const char* nA = has_next ? (const char*)g.A + (size_t)nxt.pm * tstep : cA; const char* nB = has_next ? (const char*)g.Bt + (size_t)nxt.pn * tstep : cB;
;         for (int t = 0; t < nt; t += 2) {
;             const bool last = (t == nt - 2);
;             const char* a1 = cA + (size_t)(t + 1) * kstep;
;             const char* a2 = last ? nA : cA + (size_t)(t + 2) * kstep; const char* b2 = last ? nB : cB + (size_t)(t + 2) * kstep;
;             const char* a3 = a2 + kstep; const char* b3 = b2 + kstep;
;             if (last && has_next) S.a_ready(nxt);
;             if constexpr (SP2) {
;             PG8_LDB(B0, 0, 0); PG8_LDB(B1, 0, 1); PG8_SCHED; PG8_LDA(At, 0, 0); PG8_STAGE(PG8_SA(1, 1), a1 + hstep, voffA);
;             PG8_WAIT_V(8); PG8_WAIT_L(0); PG8_BAR; PG8_MMA(0, 0, At, B0); PG8_MMA(0, 1, At, B1); PG8_BAR; PG8_SCHED;
;             PG8_LDA(At, 0, 1); PG8_STAGE(PG8_SB(0, 0), b2, voffB); PG8_STAGE(PG8_SB(0, 1), b2 + hstep, voffB); PG8_STAGE(PG8_SA(0, 0), a2, voffA);
;             PG8_WAIT_V(8); PG8_WAIT_L(0); PG8_BAR; PG8_MMA(1, 0, At, B0); PG8_MMA(1, 1, At, B1); PG8_BAR; PG8_SCHED;
;     ...
;         for (int a = 0; a < 2; ++a)
; #pragma unroll
;             for (int b = 0; b < 2; ++b)
; #pragma unroll
;                 for (int m = 0; m < 4; ++m)
; #pragma unroll
;                     for (int n = 0; n < 2; ++n) acc[a][b][m][n] = (f32x4){0.f, 0.f, 0.f, 0.f};
;         cur = nxt; cA = nA; cB = nB; ++ui;
.LBB0_91:
	s_ashr_i32 s11, s10, 31
	s_lshl_b64 s[42:43], s[10:11], 19
	s_add_u32 s72, s1, s42
	s_addc_u32 s73, s2, s43
	s_and_b64 s[42:43], s[4:5], exec
	s_cselect_b32 s11, s73, s7
	s_cselect_b32 s42, s72, s6
	s_ashr_i32 s71, s70, 31
	s_lshl_b64 s[58:59], s[70:71], 19
	s_add_u32 s74, s3, s58
	s_addc_u32 s75, s20, s59
	s_and_b64 s[58:59], s[4:5], exec
	s_cselect_b32 s43, s75, s79
	s_cselect_b32 s58, s74, s78
	s_add_u32 s6, s6, 0x40080
	s_addc_u32 s7, s7, 0
	s_add_u32 s59, s78, 0x100
	v_mov_b32_e32 v2, 0
	s_addc_u32 s60, s79, 0
	s_mov_b32 s61, -2
	v_mov_b32_e32 v3, v2
	v_mov_b64_e32 v[4:5], 0
	v_mov_b64_e32 v[6:7], 0
	v_mov_b64_e32 v[8:9], 0
	v_mov_b64_e32 v[18:19], 0
	v_mov_b64_e32 v[20:21], 0
	v_mov_b64_e32 v[22:23], 0
	v_mov_b64_e32 v[24:25], 0
	v_mov_b64_e32 v[34:35], 0
	v_mov_b64_e32 v[36:37], 0
	v_mov_b64_e32 v[38:39], 0
	v_mov_b64_e32 v[40:41], 0
	v_mov_b64_e32 v[50:51], 0
	v_mov_b64_e32 v[52:53], 0
	v_mov_b64_e32 v[54:55], 0
	v_mov_b64_e32 v[56:57], 0
	v_mov_b64_e32 v[10:11], 0
	s_waitcnt lgkmcnt(0)
	v_mov_b64_e32 v[12:13], 0
	v_mov_b64_e32 v[14:15], 0
	v_mov_b64_e32 v[16:17], 0
	v_mov_b64_e32 v[26:27], 0
	v_mov_b64_e32 v[28:29], 0
	v_mov_b64_e32 v[30:31], 0
	v_mov_b64_e32 v[32:33], 0
	v_mov_b64_e32 v[42:43], 0
	v_mov_b64_e32 v[44:45], 0
	v_mov_b64_e32 v[46:47], 0
	v_mov_b64_e32 v[48:49], 0
	v_mov_b64_e32 v[58:59], 0
	v_mov_b64_e32 v[60:61], 0
	v_mov_b64_e32 v[62:63], 0
	v_mov_b64_e32 v[64:65], 0
	v_mov_b64_e32 v[66:67], 0
	v_mov_b64_e32 v[68:69], 0
	v_mov_b64_e32 v[70:71], 0
	v_mov_b64_e32 v[72:73], 0
	v_mov_b64_e32 v[82:83], 0
	v_mov_b64_e32 v[84:85], 0
	v_mov_b64_e32 v[86:87], 0
	v_mov_b64_e32 v[88:89], 0
	v_mov_b64_e32 v[98:99], 0
	v_mov_b64_e32 v[100:101], 0
	v_mov_b64_e32 v[102:103], 0
	v_mov_b64_e32 v[104:105], 0
	v_mov_b64_e32 v[114:115], 0
	v_mov_b64_e32 v[116:117], 0
	v_mov_b64_e32 v[118:119], 0
	v_mov_b64_e32 v[120:121], 0
	v_mov_b64_e32 v[74:75], 0
	v_mov_b64_e32 v[76:77], 0
	v_mov_b64_e32 v[78:79], 0
	v_mov_b64_e32 v[80:81], 0
	v_mov_b64_e32 v[90:91], 0
	v_mov_b64_e32 v[92:93], 0
	v_mov_b64_e32 v[94:95], 0
	v_mov_b64_e32 v[96:97], 0
	v_mov_b64_e32 v[106:107], 0
	v_mov_b64_e32 v[108:109], 0
	v_mov_b64_e32 v[110:111], 0
	v_mov_b64_e32 v[112:113], 0
	v_mov_b64_e32 v[122:123], 0
	v_mov_b64_e32 v[124:125], 0
	v_mov_b64_e32 v[126:127], 0
	v_mov_b64_e32 v[128:129], 0
.LBB0_92:
	s_add_u32 s62, s6, 0xfffc0080
	s_addc_u32 s63, s7, -1
	s_add_i32 s64, 0, 0x10000
	s_cmp_eq_u32 s61, 12
	s_cselect_b32 s81, s11, s63
	s_cselect_b32 s80, s42, s62
	s_cselect_b32 s79, s43, s60
	s_cselect_b32 s78, s58, s59
	s_add_i32 s71, 0, 0x14000
	v_add_u32_e32 v142, s64, v171
	v_add_u32_e32 v183, s71, v171
	ds_read_b128 v[130:133], v142
	ds_read_b128 v[134:137], v142 offset:1024
	ds_read_b128 v[138:141], v142 offset:2048
	ds_read_b128 v[142:145], v142 offset:3072
	ds_read_b128 v[162:165], v183
	ds_read_b128 v[166:169], v183 offset:1024
	ds_read_b128 v[184:187], v183 offset:2048
	ds_read_b128 v[188:191], v183 offset:3072
	s_add_i32 m0, s26, 0xc000
	ds_read_b128 v[192:195], v174
	ds_read_b128 v[196:199], v174 offset:1024
	ds_read_b128 v[200:203], v174 offset:2048
	ds_read_b128 v[204:207], v174 offset:3072
	ds_read_b128 v[208:211], v174 offset:4096
	ds_read_b128 v[212:215], v174 offset:5120
	ds_read_b128 v[216:219], v174 offset:6144
	ds_read_b128 v[220:223], v174 offset:7168
	global_load_lds_dwordx4 v156, s[6:7]
	s_add_i32 m0, s26, 0xe000
	s_nop 0
	global_load_lds_dwordx4 v158, s[6:7]
	s_cmp_lg_u32 s61, -2
	s_cbranch_scc1 .Lra_n_q1
	s_cmp_lt_u32 s37, 2
	s_cbranch_scc1 .Lra_n_q1
	s_waitcnt vmcnt(32)
	s_branch .Lra_d_q1
.Lra_n_q1:
	s_waitcnt vmcnt(8)
.Lra_d_q1:
	s_waitcnt lgkmcnt(0)
	s_barrier
	s_setprio 1
	s_waitcnt lgkmcnt(0)
	v_mfma_f32_16x16x32_bf16 v[126:129], v[130:133], v[192:195], v[126:129]
	v_mfma_f32_16x16x32_bf16 v[122:125], v[138:141], v[192:195], v[122:125]
	v_mfma_f32_16x16x32_bf16 v[110:113], v[130:133], v[200:203], v[110:113]
	v_mfma_f32_16x16x32_bf16 v[106:109], v[138:141], v[200:203], v[106:109]
	v_mfma_f32_16x16x32_bf16 v[94:97], v[130:133], v[208:211], v[94:97]
	v_mfma_f32_16x16x32_bf16 v[90:93], v[138:141], v[208:211], v[90:93]
	v_mfma_f32_16x16x32_bf16 v[78:81], v[130:133], v[216:219], v[78:81]
	v_mfma_f32_16x16x32_bf16 v[74:77], v[138:141], v[216:219], v[74:77]
	v_mfma_f32_16x16x32_bf16 v[126:129], v[134:137], v[196:199], v[126:129]
	v_mfma_f32_16x16x32_bf16 v[122:125], v[142:145], v[196:199], v[122:125]
	v_mfma_f32_16x16x32_bf16 v[110:113], v[134:137], v[204:207], v[110:113]
	v_mfma_f32_16x16x32_bf16 v[106:109], v[142:145], v[204:207], v[106:109]
	v_mfma_f32_16x16x32_bf16 v[94:97], v[134:137], v[212:215], v[94:97]
	v_mfma_f32_16x16x32_bf16 v[90:93], v[142:145], v[212:215], v[90:93]
	v_mfma_f32_16x16x32_bf16 v[78:81], v[134:137], v[220:223], v[78:81]
	v_mfma_f32_16x16x32_bf16 v[74:77], v[142:145], v[220:223], v[74:77]
	s_setprio 0
	s_setprio 1
	v_mfma_f32_16x16x32_bf16 v[118:121], v[162:165], v[192:195], v[118:121]
	v_mfma_f32_16x16x32_bf16 v[114:117], v[184:187], v[192:195], v[114:117]
	v_mfma_f32_16x16x32_bf16 v[102:105], v[162:165], v[200:203], v[102:105]
	v_mfma_f32_16x16x32_bf16 v[98:101], v[184:187], v[200:203], v[98:101]
	v_mfma_f32_16x16x32_bf16 v[86:89], v[162:165], v[208:211], v[86:89]
	v_mfma_f32_16x16x32_bf16 v[82:85], v[184:187], v[208:211], v[82:85]
	v_mfma_f32_16x16x32_bf16 v[70:73], v[162:165], v[216:219], v[70:73]
	v_mfma_f32_16x16x32_bf16 v[66:69], v[184:187], v[216:219], v[66:69]
	v_mfma_f32_16x16x32_bf16 v[118:121], v[166:169], v[196:199], v[118:121]
	v_mfma_f32_16x16x32_bf16 v[114:117], v[188:191], v[196:199], v[114:117]
	v_mfma_f32_16x16x32_bf16 v[102:105], v[166:169], v[204:207], v[102:105]
	v_mfma_f32_16x16x32_bf16 v[98:101], v[188:191], v[204:207], v[98:101]
	v_mfma_f32_16x16x32_bf16 v[86:89], v[166:169], v[212:215], v[86:89]
	v_mfma_f32_16x16x32_bf16 v[82:85], v[188:191], v[212:215], v[82:85]
	v_mfma_f32_16x16x32_bf16 v[70:73], v[166:169], v[220:223], v[70:73]
	v_mfma_f32_16x16x32_bf16 v[66:69], v[188:191], v[220:223], v[66:69]
	s_setprio 0
	s_barrier
	s_add_i32 s62, s64, s21
	s_mov_b32 m0, s62
	ds_read_b128 v[192:195], v174 offset:16384
	ds_read_b128 v[196:199], v174 offset:17408
	ds_read_b128 v[200:203], v174 offset:18432
	ds_read_b128 v[204:207], v174 offset:19456
	ds_read_b128 v[208:211], v174 offset:20480
	ds_read_b128 v[212:215], v174 offset:21504
	ds_read_b128 v[216:219], v174 offset:22528
	ds_read_b128 v[220:223], v174 offset:23552
	global_load_lds_dwordx4 v0, s[78:79]
	s_add_i32 m0, s62, 0x2000
	s_add_u32 s62, s78, 0x40000
	s_addc_u32 s63, s79, 0
	s_add_i32 s64, s71, s21
	global_load_lds_dwordx4 v150, s[78:79]
	s_mov_b32 m0, s64
	s_nop 0
	global_load_lds_dwordx4 v0, s[62:63]
	s_add_i32 m0, s64, 0x2000
	s_nop 0
	global_load_lds_dwordx4 v150, s[62:63]
	s_mov_b32 m0, s26
	s_nop 0
	global_load_lds_dwordx4 v146, s[80:81]
	s_mov_b32 m0, s27
	s_nop 0
	global_load_lds_dwordx4 v148, s[80:81]
	s_cmp_lg_u32 s61, -2
	s_cbranch_scc1 .Lra_n_q2
	s_cmp_lt_u32 s37, 2
	s_cbranch_scc1 .Lra_n_q2
	s_waitcnt vmcnt(32)
	s_branch .Lra_d_q2

; #define PG8_STAGE(bufoff, gbase, voff) do { _Pragma("unroll") for (int _i = 0; _i < 2; ++_i) \
;         __builtin_amdgcn_global_load_lds((const unsigned*)((const char*)(gbase) + (voff)[_i]), (PG8_LAS unsigned*)(lds + (bufoff) + ldsw + _i * 8192), 16, 0, 0); } while (0)
; #define PG8_LDA(dst, b, h) do { _Pragma("unroll") for (int m = 0; m < 4; ++m) _Pragma("unroll") for (int k = 0; k < 2; ++k) dst[m][k] = *(const PG8_LAS bf16x8*)(lds + PG8_SA(b, h) + aoff + m * 2048 + k * 1024); } while (0)
; #define PG8_LDB(dst, b, h) do { _Pragma("unroll") for (int n = 0; n < 2; ++n) _Pragma("unroll") for (int k = 0; k < 2; ++k) dst[n][k] = *(const PG8_LAS bf16x8*)(lds + PG8_SB(b, h) + boff + n * 2048 + k * 1024); } while (0)
; #define PG8_MMA(ai, bj, At, Bt) do { __builtin_amdgcn_s_setprio(1); _Pragma("unroll") for (int m = 0; m < 4; ++m) _Pragma("unroll") for (int n = 0; n < 2; ++n) _Pragma("unroll") for (int k = 0; k < 2; ++k) \
;         acc[ai][bj][m][n] = __builtin_amdgcn_mfma_f32_16x16x32_bf16(Bt[n][k], At[m][k], acc[ai][bj][m][n], 0, 0, 0); __builtin_amdgcn_s_setprio(0); } while (0)
; #define PG8_BAR __builtin_amdgcn_s_barrier()
; template <class Epi, class Sched, bool ALIGN_EPI = false, bool SP2 = false>
; __device__ __forceinline__ void gemm_phase(PG8_LAS unsigned char* lds, const Gemm g, const Sched& S, const Epi& E, const int tid_in) {
;     ...
;             PG8_LDB(B0, 0, 0); PG8_LDB(B1, 0, 1); PG8_SCHED; PG8_LDA(At, 0, 0); PG8_STAGE(PG8_SA(1, 1), a1 + hstep, voffA);
;             PG8_WAIT_V(8); PG8_WAIT_L(0); PG8_BAR; PG8_MMA(0, 0, At, B0); PG8_MMA(0, 1, At, B1); PG8_BAR; PG8_SCHED;
;             PG8_LDA(At, 0, 1); PG8_STAGE(PG8_SB(0, 0), b2, voffB); PG8_STAGE(PG8_SB(0, 1), b2 + hstep, voffB); PG8_STAGE(PG8_SA(0, 0), a2, voffA);
;             PG8_WAIT_V(8); PG8_WAIT_L(0); PG8_BAR; PG8_MMA(1, 0, At, B0); PG8_MMA(1, 1, At, B1); PG8_BAR; PG8_SCHED;
;             PG8_LDB(B0, 1, 0); PG8_LDB(B1, 1, 1); PG8_SCHED; PG8_LDA(At, 1, 0); PG8_STAGE(PG8_SA(0, 1), a2 + hstep, voffA);
;             PG8_WAIT_V(8); PG8_WAIT_L(0); PG8_BAR; PG8_MMA(0, 0, At, B0); PG8_MMA(0, 1, At, B1); PG8_BAR; PG8_SCHED;
;             PG8_LDA(At, 1, 1); PG8_STAGE(PG8_SB(1, 0), b3, voffB); PG8_STAGE(PG8_SB(1, 1), b3 + hstep, voffB); PG8_STAGE(PG8_SA(1, 0), a3, voffA);
;             PG8_WAIT_V(8); PG8_WAIT_L(0); PG8_BAR; PG8_MMA(1, 0, At, B0); PG8_MMA(1, 1, At, B1); PG8_BAR; PG8_SCHED;
.Lra_d_q2:
	s_waitcnt lgkmcnt(0)
	s_barrier
	s_setprio 1
	s_waitcnt lgkmcnt(0)
	v_mfma_f32_16x16x32_bf16 v[62:65], v[130:133], v[192:195], v[62:65]
	v_mfma_f32_16x16x32_bf16 v[58:61], v[138:141], v[192:195], v[58:61]
	v_mfma_f32_16x16x32_bf16 v[46:49], v[130:133], v[200:203], v[46:49]
	v_mfma_f32_16x16x32_bf16 v[42:45], v[138:141], v[200:203], v[42:45]
	v_mfma_f32_16x16x32_bf16 v[30:33], v[130:133], v[208:211], v[30:33]
	v_mfma_f32_16x16x32_bf16 v[26:29], v[138:141], v[208:211], v[26:29]
	v_mfma_f32_16x16x32_bf16 v[14:17], v[130:133], v[216:219], v[14:17]
	v_mfma_f32_16x16x32_bf16 v[10:13], v[138:141], v[216:219], v[10:13]
	v_mfma_f32_16x16x32_bf16 v[62:65], v[134:137], v[196:199], v[62:65]
	v_mfma_f32_16x16x32_bf16 v[58:61], v[142:145], v[196:199], v[58:61]
	v_mfma_f32_16x16x32_bf16 v[46:49], v[134:137], v[204:207], v[46:49]
	v_mfma_f32_16x16x32_bf16 v[42:45], v[142:145], v[204:207], v[42:45]
	v_mfma_f32_16x16x32_bf16 v[30:33], v[134:137], v[212:215], v[30:33]
	v_mfma_f32_16x16x32_bf16 v[26:29], v[142:145], v[212:215], v[26:29]
	v_mfma_f32_16x16x32_bf16 v[14:17], v[134:137], v[220:223], v[14:17]
	v_mfma_f32_16x16x32_bf16 v[10:13], v[142:145], v[220:223], v[10:13]
	s_setprio 0
	s_setprio 1
	v_mfma_f32_16x16x32_bf16 v[54:57], v[162:165], v[192:195], v[54:57]
	v_mfma_f32_16x16x32_bf16 v[50:53], v[184:187], v[192:195], v[50:53]
	v_mfma_f32_16x16x32_bf16 v[38:41], v[162:165], v[200:203], v[38:41]
	v_mfma_f32_16x16x32_bf16 v[34:37], v[184:187], v[200:203], v[34:37]
	v_mfma_f32_16x16x32_bf16 v[22:25], v[162:165], v[208:211], v[22:25]
	v_mfma_f32_16x16x32_bf16 v[18:21], v[184:187], v[208:211], v[18:21]
	v_mfma_f32_16x16x32_bf16 v[6:9], v[162:165], v[216:219], v[6:9]
	v_mfma_f32_16x16x32_bf16 v[2:5], v[184:187], v[216:219], v[2:5]
	v_mfma_f32_16x16x32_bf16 v[54:57], v[166:169], v[196:199], v[54:57]
	v_mfma_f32_16x16x32_bf16 v[50:53], v[188:191], v[196:199], v[50:53]
	v_mfma_f32_16x16x32_bf16 v[38:41], v[166:169], v[204:207], v[38:41]
	v_mfma_f32_16x16x32_bf16 v[34:37], v[188:191], v[204:207], v[34:37]
	v_mfma_f32_16x16x32_bf16 v[22:25], v[166:169], v[212:215], v[22:25]
	v_mfma_f32_16x16x32_bf16 v[18:21], v[188:191], v[212:215], v[18:21]
	v_mfma_f32_16x16x32_bf16 v[6:9], v[166:169], v[220:223], v[6:9]
	v_mfma_f32_16x16x32_bf16 v[2:5], v[188:191], v[220:223], v[2:5]
	s_setprio 0
	s_barrier
	s_add_i32 s64, 0, 0x18000
	s_add_i32 s71, 0, 0x1c000
	v_add_u32_e32 v142, s64, v171
	v_add_u32_e32 v183, s71, v171
	ds_read_b128 v[130:133], v142
	ds_read_b128 v[134:137], v142 offset:1024
	ds_read_b128 v[138:141], v142 offset:2048
	ds_read_b128 v[142:145], v142 offset:3072
	ds_read_b128 v[162:165], v183
	ds_read_b128 v[166:169], v183 offset:1024
	ds_read_b128 v[184:187], v183 offset:2048
	ds_read_b128 v[188:191], v183 offset:3072
	s_add_u32 s62, s80, 0x40000
	s_addc_u32 s63, s81, 0
	s_mov_b32 m0, s29
	ds_read_b128 v[192:195], v174 offset:32768
	ds_read_b128 v[196:199], v174 offset:33792
	ds_read_b128 v[200:203], v174 offset:34816
	ds_read_b128 v[204:207], v174 offset:35840
	ds_read_b128 v[208:211], v174 offset:36864
	ds_read_b128 v[212:215], v174 offset:37888
	ds_read_b128 v[216:219], v174 offset:38912
	ds_read_b128 v[220:223], v174 offset:39936
	global_load_lds_dwordx4 v146, s[62:63]
	s_mov_b32 m0, s34
	s_nop 0
	global_load_lds_dwordx4 v148, s[62:63]
	s_waitcnt vmcnt(8)
	s_waitcnt lgkmcnt(0)
	s_barrier
	s_setprio 1
	s_waitcnt lgkmcnt(0)
	v_mfma_f32_16x16x32_bf16 v[126:129], v[130:133], v[192:195], v[126:129]
	v_mfma_f32_16x16x32_bf16 v[122:125], v[138:141], v[192:195], v[122:125]
	v_mfma_f32_16x16x32_bf16 v[110:113], v[130:133], v[200:203], v[110:113]
	v_mfma_f32_16x16x32_bf16 v[106:109], v[138:141], v[200:203], v[106:109]
	v_mfma_f32_16x16x32_bf16 v[94:97], v[130:133], v[208:211], v[94:97]
	v_mfma_f32_16x16x32_bf16 v[90:93], v[138:141], v[208:211], v[90:93]
	v_mfma_f32_16x16x32_bf16 v[78:81], v[130:133], v[216:219], v[78:81]
	v_mfma_f32_16x16x32_bf16 v[74:77], v[138:141], v[216:219], v[74:77]
	v_mfma_f32_16x16x32_bf16 v[126:129], v[134:137], v[196:199], v[126:129]
	v_mfma_f32_16x16x32_bf16 v[122:125], v[142:145], v[196:199], v[122:125]
	v_mfma_f32_16x16x32_bf16 v[110:113], v[134:137], v[204:207], v[110:113]
	v_mfma_f32_16x16x32_bf16 v[106:109], v[142:145], v[204:207], v[106:109]
	v_mfma_f32_16x16x32_bf16 v[94:97], v[134:137], v[212:215], v[94:97]
	v_mfma_f32_16x16x32_bf16 v[90:93], v[142:145], v[212:215], v[90:93]
	v_mfma_f32_16x16x32_bf16 v[78:81], v[134:137], v[220:223], v[78:81]
	v_mfma_f32_16x16x32_bf16 v[74:77], v[142:145], v[220:223], v[74:77]
	s_setprio 0
	s_setprio 1
	v_mfma_f32_16x16x32_bf16 v[118:121], v[162:165], v[192:195], v[118:121]
	v_mfma_f32_16x16x32_bf16 v[114:117], v[184:187], v[192:195], v[114:117]
	v_mfma_f32_16x16x32_bf16 v[102:105], v[162:165], v[200:203], v[102:105]
	v_mfma_f32_16x16x32_bf16 v[98:101], v[184:187], v[200:203], v[98:101]
	v_mfma_f32_16x16x32_bf16 v[86:89], v[162:165], v[208:211], v[86:89]
	v_mfma_f32_16x16x32_bf16 v[82:85], v[184:187], v[208:211], v[82:85]
	v_mfma_f32_16x16x32_bf16 v[70:73], v[162:165], v[216:219], v[70:73]
	v_mfma_f32_16x16x32_bf16 v[66:69], v[184:187], v[216:219], v[66:69]
	v_mfma_f32_16x16x32_bf16 v[118:121], v[166:169], v[196:199], v[118:121]
	v_mfma_f32_16x16x32_bf16 v[114:117], v[188:191], v[196:199], v[114:117]
	v_mfma_f32_16x16x32_bf16 v[102:105], v[166:169], v[204:207], v[102:105]
	v_mfma_f32_16x16x32_bf16 v[98:101], v[188:191], v[204:207], v[98:101]
	v_mfma_f32_16x16x32_bf16 v[86:89], v[166:169], v[212:215], v[86:89]
	v_mfma_f32_16x16x32_bf16 v[82:85], v[188:191], v[212:215], v[82:85]
	v_mfma_f32_16x16x32_bf16 v[70:73], v[166:169], v[220:223], v[70:73]
	v_mfma_f32_16x16x32_bf16 v[66:69], v[188:191], v[220:223], v[66:69]
	s_setprio 0
	s_barrier
; #define PG8_STAGE(bufoff, gbase, voff) do { _Pragma("unroll") for (int _i = 0; _i < 2; ++_i) \
;         __builtin_amdgcn_global_load_lds((const unsigned*)((const char*)(gbase) + (voff)[_i]), (PG8_LAS unsigned*)(lds + (bufoff) + ldsw + _i * 8192), 16, 0, 0); } while (0)
; #define PG8_LDA(dst, b, h) do { _Pragma("unroll") for (int m = 0; m < 4; ++m) _Pragma("unroll") for (int k = 0; k < 2; ++k) dst[m][k] = *(const PG8_LAS bf16x8*)(lds + PG8_SA(b, h) + aoff + m * 2048 + k * 1024); } while (0)
; #define PG8_MMA(ai, bj, At, Bt) do { __builtin_amdgcn_s_setprio(1); _Pragma("unroll") for (int m = 0; m < 4; ++m) _Pragma("unroll") for (int n = 0; n < 2; ++n) _Pragma("unroll") for (int k = 0; k < 2; ++k) \
;         acc[ai][bj][m][n] = __builtin_amdgcn_mfma_f32_16x16x32_bf16(Bt[n][k], At[m][k], acc[ai][bj][m][n], 0, 0, 0); __builtin_amdgcn_s_setprio(0); } while (0)
; #define PG8_WAIT_V(n) asm volatile("s_waitcnt vmcnt(" #n ")" ::: "memory")
; #define PG8_WAIT_L(n) asm volatile("s_waitcnt lgkmcnt(" #n ")" ::: "memory")
; #define PG8_BAR __builtin_amdgcn_s_barrier()
; #define PG8_SCHED __builtin_amdgcn_sched_barrier(0)
; template <class Epi, class Sched, bool ALIGN_EPI = false, bool SP2 = false>
; __device__ __forceinline__ void gemm_phase(PG8_LAS unsigned char* lds, const Gemm g, const Sched& S, const Epi& E, const int tid_in) {
;     ...
;             PG8_LDA(At, 1, 1); PG8_STAGE(PG8_SB(1, 0), b3, voffB); PG8_STAGE(PG8_SB(1, 1), b3 + hstep, voffB); PG8_STAGE(PG8_SA(1, 0), a3, voffA);
;             PG8_WAIT_V(8); PG8_WAIT_L(0); PG8_BAR; PG8_MMA(1, 0, At, B0); PG8_MMA(1, 1, At, B1); PG8_BAR; PG8_SCHED;
	s_add_i32 s62, s64, s21
	s_mov_b32 m0, s62
	ds_read_b128 v[192:195], v174 offset:49152
	ds_read_b128 v[196:199], v174 offset:50176
	ds_read_b128 v[200:203], v174 offset:51200
	ds_read_b128 v[204:207], v174 offset:52224
	ds_read_b128 v[208:211], v174 offset:53248
	ds_read_b128 v[212:215], v174 offset:54272
	ds_read_b128 v[216:219], v174 offset:55296
	ds_read_b128 v[220:223], v174 offset:56320
	s_add_u32 s44, s78, 0x80
	s_addc_u32 s45, s79, 0
	global_load_lds_dwordx4 v0, s[44:45]
	s_add_i32 m0, s62, 0x2000
	s_add_u32 s62, s78, 0x40080
	s_addc_u32 s63, s79, 0
	s_add_i32 s64, s71, s21
	global_load_lds_dwordx4 v150, s[44:45]
	s_mov_b32 m0, s64
	s_nop 0
	global_load_lds_dwordx4 v0, s[62:63]
	s_add_i32 m0, s64, 0x2000
	s_nop 0
	global_load_lds_dwordx4 v150, s[62:63]
	s_mov_b32 m0, s35
	s_nop 0
	s_add_u32 s44, s80, 0x80
	s_addc_u32 s45, s81, 0
	global_load_lds_dwordx4 v146, s[44:45]
	s_mov_b32 m0, s36
	s_nop 0
	global_load_lds_dwordx4 v148, s[44:45]
	s_waitcnt vmcnt(8)
	s_waitcnt lgkmcnt(0)
	s_barrier
	s_setprio 1
	s_waitcnt lgkmcnt(0)
	v_mfma_f32_16x16x32_bf16 v[62:65], v[130:133], v[192:195], v[62:65]
	v_mfma_f32_16x16x32_bf16 v[58:61], v[138:141], v[192:195], v[58:61]
	v_mfma_f32_16x16x32_bf16 v[46:49], v[130:133], v[200:203], v[46:49]
	v_mfma_f32_16x16x32_bf16 v[42:45], v[138:141], v[200:203], v[42:45]
	v_mfma_f32_16x16x32_bf16 v[30:33], v[130:133], v[208:211], v[30:33]
	v_mfma_f32_16x16x32_bf16 v[26:29], v[138:141], v[208:211], v[26:29]
	v_mfma_f32_16x16x32_bf16 v[14:17], v[130:133], v[216:219], v[14:17]
	v_mfma_f32_16x16x32_bf16 v[10:13], v[138:141], v[216:219], v[10:13]
	v_mfma_f32_16x16x32_bf16 v[62:65], v[134:137], v[196:199], v[62:65]
	v_mfma_f32_16x16x32_bf16 v[58:61], v[142:145], v[196:199], v[58:61]
	v_mfma_f32_16x16x32_bf16 v[46:49], v[134:137], v[204:207], v[46:49]
	v_mfma_f32_16x16x32_bf16 v[42:45], v[142:145], v[204:207], v[42:45]
	v_mfma_f32_16x16x32_bf16 v[30:33], v[134:137], v[212:215], v[30:33]
	v_mfma_f32_16x16x32_bf16 v[26:29], v[142:145], v[212:215], v[26:29]
	v_mfma_f32_16x16x32_bf16 v[14:17], v[134:137], v[220:223], v[14:17]
	v_mfma_f32_16x16x32_bf16 v[10:13], v[142:145], v[220:223], v[10:13]
	s_setprio 0
	s_setprio 1
	v_mfma_f32_16x16x32_bf16 v[54:57], v[162:165], v[192:195], v[54:57]
	v_mfma_f32_16x16x32_bf16 v[50:53], v[184:187], v[192:195], v[50:53]
	v_mfma_f32_16x16x32_bf16 v[38:41], v[162:165], v[200:203], v[38:41]
	v_mfma_f32_16x16x32_bf16 v[34:37], v[184:187], v[200:203], v[34:37]
	v_mfma_f32_16x16x32_bf16 v[22:25], v[162:165], v[208:211], v[22:25]
	v_mfma_f32_16x16x32_bf16 v[18:21], v[184:187], v[208:211], v[18:21]
	v_mfma_f32_16x16x32_bf16 v[6:9], v[162:165], v[216:219], v[6:9]
	v_mfma_f32_16x16x32_bf16 v[2:5], v[184:187], v[216:219], v[2:5]
	v_mfma_f32_16x16x32_bf16 v[54:57], v[166:169], v[196:199], v[54:57]
	v_mfma_f32_16x16x32_bf16 v[50:53], v[188:191], v[196:199], v[50:53]
	v_mfma_f32_16x16x32_bf16 v[38:41], v[166:169], v[204:207], v[38:41]
	v_mfma_f32_16x16x32_bf16 v[34:37], v[188:191], v[204:207], v[34:37]
	v_mfma_f32_16x16x32_bf16 v[22:25], v[166:169], v[212:215], v[22:25]
	v_mfma_f32_16x16x32_bf16 v[18:21], v[188:191], v[212:215], v[18:21]
	v_mfma_f32_16x16x32_bf16 v[6:9], v[166:169], v[220:223], v[6:9]
	v_mfma_f32_16x16x32_bf16 v[2:5], v[188:191], v[220:223], v[2:5]
	s_setprio 0
	s_barrier
	s_add_i32 s61, s61, 2
	s_add_u32 s6, s6, 0x100
	s_addc_u32 s7, s7, 0
	s_add_u32 s59, s59, 0x100
	s_addc_u32 s60, s60, 0
	s_cmp_gt_u32 s61, 13
	s_cbranch_scc0 .LBB0_92
	s_mov_b64 s[44:45], 0x80
	s_and_b64 vcc, exec, s[66:67]
	s_cbranch_vccz .LBB0_95
	s_barrier

; __device__ __forceinline__ unsigned cvt_pk_bf16(float lo, float hi) { unsigned r; asm volatile("v_cvt_pk_bf16_f32 %0, %1, %2" : "=v"(r) : "v"(lo), "v"(hi)); return r; }
;     __device__ __forceinline__ void operator()(const f32x4 (&acc)[2][2][4][2], const Unit& u, int wr, int wc, int fr, int fq, const float (&rsv)[8]) const {
;         const int row0 = u.pm * BM + wr * 64 + fr, col0 = u.pn * BM + wc * 32 + 8 * fq;
;         const bool isq = (u.pn < 2) || (u.pn == 6) || (u.pn == 7);
;         const float sc = isq ? QSCALE : 1.f;
;         const bool rotw = (u.pn < 4) && ((wc & 1) == 0);
;         const float sgn = (fq == 0) ? -1.f : 1.f; const bool rotl = fq < 2; const int pidx = (((fq ^ 1) << 4) | fr) << 2;
; #pragma unroll
;         for (int ai = 0; ai < 2; ++ai)
; #pragma unroll
;             for (int m = 0; m < 4; ++m) { const int row = row0 + ai * HALF + m * 16; bf16_t* rowp = O + (size_t)row * 3072 + col0; const float scr_ = sc * rsv[ai * 4 + m];
;                 f32x4 c0 = {1.f, 1.f, 1.f, 1.f}, c1 = c0, s0 = {0.f, 0.f, 0.f, 0.f}, s1 = s0;
;                 if (rotw) { const f32x4* rp = (const f32x4*)(rot + (size_t)row * 16); c0 = rp[0]; c1 = rp[1]; s0 = rp[2]; s1 = rp[3]; }
; #pragma unroll
;                 for (int bj = 0; bj < 2; ++bj) { f32x4 v0 = acc[ai][bj][m][0], v1 = acc[ai][bj][m][1];
;                     if (rotw) { f32x4 p0, p1;
; #pragma unroll
;                         for (int j = 0; j < 4; ++j) { const float a0 = v0[j], a1 = v1[j]; p0[j] = __int_as_float(__builtin_amdgcn_ds_bpermute(pidx, __float_as_int(a0))); p1[j] = __int_as_float(__builtin_amdgcn_ds_bpermute(pidx, __float_as_int(a1))); }
;                         if (rotl) { v0 = v0 * c0 + (p0 * s0) * sgn; v1 = v1 * c1 + (p1 * s1) * sgn; } }
;                     v0 = v0 * scr_; v1 = v1 * scr_; u32x4 w; w.x = cvt_pk_bf16(v0[0], v0[1]); w.y = cvt_pk_bf16(v0[2], v0[3]); w.z = cvt_pk_bf16(v1[0], v1[1]); w.w = cvt_pk_bf16(v1[2], v1[3]);
;                     *(u32x4*)(rowp + bj * HALF) = w; } }
.LBB0_101:
	s_cmp_lt_i32 s76, 2
	s_cselect_b64 s[42:43], -1, 0
	s_and_b32 s11, s76, -2
	s_cmp_eq_u32 s11, 6
	s_cselect_b64 s[58:59], -1, 0
	s_or_b64 vcc, s[42:43], s[58:59]
	v_cndmask_b32_e32 v161, 1.0, v238, vcc
	s_waitcnt lgkmcnt(0)
	v_lshl_or_b32 v162, s76, 8, v172
	v_mov_b64_e32 v[164:165], s[14:15]
	s_waitcnt vmcnt(8)
	v_mul_f32_e32 v166, v161, v182
	v_ashrrev_i32_e32 v163, 31, v162
	v_mad_i64_i32 v[164:165], s[42:43], v160, s97, v[164:165]
	v_lshl_add_u64 v[164:165], v[162:163], 1, v[164:165]
	v_pk_mul_f32 v[168:169], v[166:167], v[124:125] op_sel_hi:[0,1]
	v_pk_mul_f32 v[124:125], v[166:167], v[122:123] op_sel_hi:[0,1]
	s_and_b64 vcc, exec, s[6:7]
	v_pk_mul_f32 v[128:129], v[166:167], v[128:129] op_sel_hi:[0,1]
	v_pk_mul_f32 v[126:127], v[166:167], v[126:127] op_sel_hi:[0,1]
	v_cvt_pk_bf16_f32 v122, v126, v127
	v_cvt_pk_bf16_f32 v123, v128, v129
	v_cvt_pk_bf16_f32 v124, v124, v125
	v_cvt_pk_bf16_f32 v125, v168, v169
	global_store_dwordx4 v[164:165], v[122:125], off
	s_cbranch_vccnz .LBB0_105
	ds_bpermute_b32 v126, v173, v118
	ds_bpermute_b32 v122, v173, v114
	ds_bpermute_b32 v127, v173, v119
	ds_bpermute_b32 v123, v173, v115
	ds_bpermute_b32 v128, v173, v120
	ds_bpermute_b32 v124, v173, v116
	ds_bpermute_b32 v129, v173, v121
	ds_bpermute_b32 v125, v173, v117
	s_and_saveexec_b64 s[76:77], s[8:9]
	s_cbranch_execz .LBB0_104
	s_waitcnt lgkmcnt(1)
	v_pk_mul_f32 v[128:129], v[144:145], v[128:129]
	v_pk_mul_f32 v[126:127], v[142:143], v[126:127]
	s_waitcnt lgkmcnt(0)
	v_pk_mul_f32 v[124:125], v[140:141], v[124:125]
	v_pk_mul_f32 v[122:123], v[138:139], v[122:123]
	v_pk_mul_f32 v[128:129], v[154:155], v[128:129]
	v_pk_mul_f32 v[126:127], v[152:153], v[126:127]
	v_pk_mul_f32 v[124:125], v[154:155], v[124:125]
	v_pk_mul_f32 v[122:123], v[152:153], v[122:123]
	v_pk_fma_f32 v[120:121], v[120:121], v[136:137], v[128:129]
	v_pk_fma_f32 v[118:119], v[118:119], v[134:135], v[126:127]
	v_pk_fma_f32 v[116:117], v[116:117], v[132:133], v[124:125]
	v_pk_fma_f32 v[114:115], v[114:115], v[130:131], v[122:123]

; #define PG8_STAGE(bufoff, gbase, voff) do { _Pragma("unroll") for (int _i = 0; _i < 2; ++_i) \
;         __builtin_amdgcn_global_load_lds((const unsigned*)((const char*)(gbase) + (voff)[_i]), (PG8_LAS unsigned*)(lds + (bufoff) + ldsw + _i * 8192), 16, 0, 0); } while (0)
; #define PG8_LDA(dst, b, h) do { _Pragma("unroll") for (int m = 0; m < 4; ++m) _Pragma("unroll") for (int k = 0; k < 2; ++k) dst[m][k] = *(const PG8_LAS bf16x8*)(lds + PG8_SA(b, h) + aoff + m * 2048 + k * 1024); } while (0)
; #define PG8_LDB(dst, b, h) do { _Pragma("unroll") for (int n = 0; n < 2; ++n) _Pragma("unroll") for (int k = 0; k < 2; ++k) dst[n][k] = *(const PG8_LAS bf16x8*)(lds + PG8_SB(b, h) + boff + n * 2048 + k * 1024); } while (0)
; #define PG8_WAIT_V(n) asm volatile("s_waitcnt vmcnt(" #n ")" ::: "memory")
; #define PG8_WAIT_L(n) asm volatile("s_waitcnt lgkmcnt(" #n ")" ::: "memory")
; template <class Epi, class Sched, bool ALIGN_EPI = false, bool SP2 = false>
; __device__ __forceinline__ void gemm_phase(PG8_LAS unsigned char* lds, const Gemm g, const Sched& S, const Epi& E, const int tid_in) {
;     ...
;         for (int t = 0; t < nt; t += 2) {
;             const bool last = (t == nt - 2);
;             const char* a1 = cA + (size_t)(t + 1) * kstep;
;             const char* a2 = last ? nA : cA + (size_t)(t + 2) * kstep; const char* b2 = last ? nB : cB + (size_t)(t + 2) * kstep;
;             const char* a3 = a2 + kstep; const char* b3 = b2 + kstep;
;             if (last && has_next) S.a_ready(nxt);
;             if constexpr (SP2) {
;             PG8_LDB(B0, 0, 0); PG8_LDB(B1, 0, 1); PG8_SCHED; PG8_LDA(At, 0, 0); PG8_STAGE(PG8_SA(1, 1), a1 + hstep, voffA);
;             PG8_WAIT_V(8); PG8_WAIT_L(0); PG8_BAR; PG8_MMA(0, 0, At, B0); PG8_MMA(0, 1, At, B1); PG8_BAR; PG8_SCHED;
;             PG8_LDA(At, 0, 1); PG8_STAGE(PG8_SB(0, 0), b2, voffB); PG8_STAGE(PG8_SB(0, 1), b2 + hstep, voffB); PG8_STAGE(PG8_SA(0, 0), a2, voffA);
;             PG8_WAIT_V(8); PG8_WAIT_L(0); PG8_BAR; PG8_MMA(1, 0, At, B0); PG8_MMA(1, 1, At, B1); PG8_BAR; PG8_SCHED;
;     ...
;         for (int a = 0; a < 2; ++a)
; #pragma unroll
;             for (int b = 0; b < 2; ++b)
; #pragma unroll
;                 for (int m = 0; m < 4; ++m)
; #pragma unroll
;                     for (int n = 0; n < 2; ++n) acc[a][b][m][n] = (f32x4){0.f, 0.f, 0.f, 0.f};
;         cur = nxt; cA = nA; cB = nB; ++ui;
.LBB0_484:
	s_ashr_i32 s15, s14, 31
	s_lshl_b64 s[18:19], s[14:15], 19
	s_add_u32 s18, s2, s18
	s_addc_u32 s19, s3, s19
	s_and_b64 s[22:23], s[4:5], exec
	s_cselect_b32 s15, s19, s69
	s_cselect_b32 s42, s18, s68
	s_ashr_i32 s13, s12, 31
	s_lshl_b64 s[22:23], s[12:13], 19
	s_add_u32 s22, s20, s22
	s_addc_u32 s23, s21, s23
	s_and_b64 s[58:59], s[4:5], exec
	s_cselect_b32 s13, s23, s71
	s_cselect_b32 s43, s22, s70
	s_add_u32 s68, s68, 0x40080
	s_addc_u32 s69, s69, 0
	s_add_u32 s58, s70, 0x100
	v_mov_b32_e32 v2, 0
	s_addc_u32 s59, s71, 0
	s_mov_b32 s60, -2
	v_mov_b32_e32 v3, v2
	v_mov_b64_e32 v[4:5], 0
	v_mov_b64_e32 v[6:7], 0
	v_mov_b64_e32 v[8:9], 0
	v_mov_b64_e32 v[10:11], 0
	v_mov_b64_e32 v[12:13], 0
	v_mov_b64_e32 v[18:19], 0
	v_mov_b64_e32 v[20:21], 0
	v_mov_b64_e32 v[26:27], 0
	v_mov_b64_e32 v[28:29], 0
	v_mov_b64_e32 v[34:35], 0
	v_mov_b64_e32 v[36:37], 0
	v_mov_b64_e32 v[42:43], 0
	v_mov_b64_e32 v[44:45], 0
	v_mov_b64_e32 v[50:51], 0
	v_mov_b64_e32 v[52:53], 0
	v_mov_b64_e32 v[14:15], 0
	v_mov_b64_e32 v[16:17], 0
	v_mov_b64_e32 v[22:23], 0
	v_mov_b64_e32 v[24:25], 0
	v_mov_b64_e32 v[30:31], 0
	v_mov_b64_e32 v[32:33], 0
	v_mov_b64_e32 v[38:39], 0
	v_mov_b64_e32 v[40:41], 0
	v_mov_b64_e32 v[46:47], 0
	v_mov_b64_e32 v[48:49], 0
	v_mov_b64_e32 v[54:55], 0
	v_mov_b64_e32 v[56:57], 0
	v_mov_b64_e32 v[58:59], 0
	v_mov_b64_e32 v[60:61], 0
	v_mov_b64_e32 v[62:63], 0
	v_mov_b64_e32 v[64:65], 0
	v_mov_b64_e32 v[66:67], 0
	v_mov_b64_e32 v[68:69], 0
	v_mov_b64_e32 v[70:71], 0
	v_mov_b64_e32 v[72:73], 0
	v_mov_b64_e32 v[74:75], 0
	v_mov_b64_e32 v[76:77], 0
	v_mov_b64_e32 v[82:83], 0
	v_mov_b64_e32 v[84:85], 0
	v_mov_b64_e32 v[90:91], 0
	v_mov_b64_e32 v[92:93], 0
	v_mov_b64_e32 v[98:99], 0
	v_mov_b64_e32 v[100:101], 0
	v_mov_b64_e32 v[106:107], 0
	v_mov_b64_e32 v[108:109], 0
	v_mov_b64_e32 v[114:115], 0
	v_mov_b64_e32 v[116:117], 0
	v_mov_b64_e32 v[78:79], 0
	v_mov_b64_e32 v[80:81], 0
	v_mov_b64_e32 v[86:87], 0
	v_mov_b64_e32 v[88:89], 0
	v_mov_b64_e32 v[94:95], 0
	v_mov_b64_e32 v[96:97], 0
	v_mov_b64_e32 v[102:103], 0
	v_mov_b64_e32 v[104:105], 0
	v_mov_b64_e32 v[110:111], 0
	v_mov_b64_e32 v[112:113], 0
	v_mov_b64_e32 v[118:119], 0
	v_mov_b64_e32 v[120:121], 0
	v_mov_b64_e32 v[122:123], 0
	v_mov_b64_e32 v[124:125], 0
	v_mov_b64_e32 v[126:127], 0
	v_mov_b64_e32 v[128:129], 0
.LBB0_485:
	s_add_u32 s61, s68, 0xfffc0080
	s_addc_u32 s62, s69, -1
	s_add_i32 s63, 0, 0x10000
	s_cmp_eq_u32 s60, 12
	s_cselect_b32 s73, s15, s62
	s_cselect_b32 s72, s42, s61
	v_add_u32_e32 v140, s63, v143
	s_cselect_b32 s71, s13, s59
	s_cselect_b32 s70, s43, s58
	s_add_i32 s61, 0, 0x14000
	ds_read_b128 v[146:149], v140
	ds_read_b128 v[150:153], v140 offset:1024
	ds_read_b128 v[154:157], v140 offset:2048
	ds_read_b128 v[158:161], v140 offset:3072
	v_add_u32_e32 v140, s61, v143
	ds_read_b128 v[162:165], v140
	ds_read_b128 v[166:169], v140 offset:1024
	ds_read_b128 v[170:173], v140 offset:2048
	ds_read_b128 v[174:177], v140 offset:3072
	s_add_i32 m0, s17, 0xc000
	ds_read_b128 v[178:181], v145
	ds_read_b128 v[182:185], v145 offset:1024
	ds_read_b128 v[186:189], v145 offset:2048
	ds_read_b128 v[190:193], v145 offset:3072
	ds_read_b128 v[194:197], v145 offset:4096
	ds_read_b128 v[198:201], v145 offset:5120
	ds_read_b128 v[202:205], v145 offset:6144
	ds_read_b128 v[206:209], v145 offset:7168
	global_load_lds_dwordx4 v136, s[68:69]
	s_add_i32 m0, s17, 0xe000
	s_nop 0
	global_load_lds_dwordx4 v138, s[68:69]
	s_cmp_lg_u32 s60, -2
	s_cbranch_scc1 .Lra_n_o1
	s_cmp_lt_u32 s37, 2
	s_cbranch_scc1 .Lra_n_o1
	s_waitcnt vmcnt(24)
	s_branch .Lra_d_o1

; #define PG8_STAGE(bufoff, gbase, voff) do { _Pragma("unroll") for (int _i = 0; _i < 2; ++_i) \
;         __builtin_amdgcn_global_load_lds((const unsigned*)((const char*)(gbase) + (voff)[_i]), (PG8_LAS unsigned*)(lds + (bufoff) + ldsw + _i * 8192), 16, 0, 0); } while (0)
; #define PG8_LDA(dst, b, h) do { _Pragma("unroll") for (int m = 0; m < 4; ++m) _Pragma("unroll") for (int k = 0; k < 2; ++k) dst[m][k] = *(const PG8_LAS bf16x8*)(lds + PG8_SA(b, h) + aoff + m * 2048 + k * 1024); } while (0)
; #define PG8_LDB(dst, b, h) do { _Pragma("unroll") for (int n = 0; n < 2; ++n) _Pragma("unroll") for (int k = 0; k < 2; ++k) dst[n][k] = *(const PG8_LAS bf16x8*)(lds + PG8_SB(b, h) + boff + n * 2048 + k * 1024); } while (0)
; #define PG8_MMA(ai, bj, At, Bt) do { __builtin_amdgcn_s_setprio(1); _Pragma("unroll") for (int m = 0; m < 4; ++m) _Pragma("unroll") for (int n = 0; n < 2; ++n) _Pragma("unroll") for (int k = 0; k < 2; ++k) \
;         acc[ai][bj][m][n] = __builtin_amdgcn_mfma_f32_16x16x32_bf16(Bt[n][k], At[m][k], acc[ai][bj][m][n], 0, 0, 0); __builtin_amdgcn_s_setprio(0); } while (0)
; #define PG8_BAR __builtin_amdgcn_s_barrier()
; template <class Epi, class Sched, bool ALIGN_EPI = false, bool SP2 = false>
; __device__ __forceinline__ void gemm_phase(PG8_LAS unsigned char* lds, const Gemm g, const Sched& S, const Epi& E, const int tid_in) {
;     ...
;             PG8_LDB(B0, 0, 0); PG8_LDB(B1, 0, 1); PG8_SCHED; PG8_LDA(At, 0, 0); PG8_STAGE(PG8_SA(1, 1), a1 + hstep, voffA);
;             PG8_WAIT_V(8); PG8_WAIT_L(0); PG8_BAR; PG8_MMA(0, 0, At, B0); PG8_MMA(0, 1, At, B1); PG8_BAR; PG8_SCHED;
;             PG8_LDA(At, 0, 1); PG8_STAGE(PG8_SB(0, 0), b2, voffB); PG8_STAGE(PG8_SB(0, 1), b2 + hstep, voffB); PG8_STAGE(PG8_SA(0, 0), a2, voffA);
;             PG8_WAIT_V(8); PG8_WAIT_L(0); PG8_BAR; PG8_MMA(1, 0, At, B0); PG8_MMA(1, 1, At, B1); PG8_BAR; PG8_SCHED;
;             PG8_LDB(B0, 1, 0); PG8_LDB(B1, 1, 1); PG8_SCHED; PG8_LDA(At, 1, 0); PG8_STAGE(PG8_SA(0, 1), a2 + hstep, voffA);
;             PG8_WAIT_V(8); PG8_WAIT_L(0); PG8_BAR; PG8_MMA(0, 0, At, B0); PG8_MMA(0, 1, At, B1); PG8_BAR; PG8_SCHED;
;             PG8_LDA(At, 1, 1); PG8_STAGE(PG8_SB(1, 0), b3, voffB); PG8_STAGE(PG8_SB(1, 1), b3 + hstep, voffB); PG8_STAGE(PG8_SA(1, 0), a3, voffA);
;             PG8_WAIT_V(8); PG8_WAIT_L(0); PG8_BAR; PG8_MMA(1, 0, At, B0); PG8_MMA(1, 1, At, B1); PG8_BAR; PG8_SCHED;
.Lra_d_o1:
	s_waitcnt lgkmcnt(0)
	s_barrier
	s_setprio 1
	s_waitcnt lgkmcnt(0)
	v_mfma_f32_16x16x32_bf16 v[126:129], v[146:149], v[178:181], v[126:129]
	v_mfma_f32_16x16x32_bf16 v[122:125], v[154:157], v[178:181], v[122:125]
	v_mfma_f32_16x16x32_bf16 v[118:121], v[146:149], v[186:189], v[118:121]
	v_mfma_f32_16x16x32_bf16 v[110:113], v[154:157], v[186:189], v[110:113]
	v_mfma_f32_16x16x32_bf16 v[102:105], v[146:149], v[194:197], v[102:105]
	v_mfma_f32_16x16x32_bf16 v[94:97], v[154:157], v[194:197], v[94:97]
	v_mfma_f32_16x16x32_bf16 v[86:89], v[146:149], v[202:205], v[86:89]
	v_mfma_f32_16x16x32_bf16 v[78:81], v[154:157], v[202:205], v[78:81]
	v_mfma_f32_16x16x32_bf16 v[126:129], v[150:153], v[182:185], v[126:129]
	v_mfma_f32_16x16x32_bf16 v[122:125], v[158:161], v[182:185], v[122:125]
	v_mfma_f32_16x16x32_bf16 v[118:121], v[150:153], v[190:193], v[118:121]
	v_mfma_f32_16x16x32_bf16 v[110:113], v[158:161], v[190:193], v[110:113]
	v_mfma_f32_16x16x32_bf16 v[102:105], v[150:153], v[198:201], v[102:105]
	v_mfma_f32_16x16x32_bf16 v[94:97], v[158:161], v[198:201], v[94:97]
	v_mfma_f32_16x16x32_bf16 v[86:89], v[150:153], v[206:209], v[86:89]
	v_mfma_f32_16x16x32_bf16 v[78:81], v[158:161], v[206:209], v[78:81]
	s_setprio 0
	s_setprio 1
	v_mfma_f32_16x16x32_bf16 v[114:117], v[162:165], v[178:181], v[114:117]
	v_mfma_f32_16x16x32_bf16 v[106:109], v[170:173], v[178:181], v[106:109]
	v_mfma_f32_16x16x32_bf16 v[98:101], v[162:165], v[186:189], v[98:101]
	v_mfma_f32_16x16x32_bf16 v[90:93], v[170:173], v[186:189], v[90:93]
	v_mfma_f32_16x16x32_bf16 v[82:85], v[162:165], v[194:197], v[82:85]
	v_mfma_f32_16x16x32_bf16 v[74:77], v[170:173], v[194:197], v[74:77]
	v_mfma_f32_16x16x32_bf16 v[70:73], v[162:165], v[202:205], v[70:73]
	v_mfma_f32_16x16x32_bf16 v[66:69], v[170:173], v[202:205], v[66:69]
	v_mfma_f32_16x16x32_bf16 v[114:117], v[166:169], v[182:185], v[114:117]
	v_mfma_f32_16x16x32_bf16 v[106:109], v[174:177], v[182:185], v[106:109]
	v_mfma_f32_16x16x32_bf16 v[98:101], v[166:169], v[190:193], v[98:101]
	v_mfma_f32_16x16x32_bf16 v[90:93], v[174:177], v[190:193], v[90:93]
	v_mfma_f32_16x16x32_bf16 v[82:85], v[166:169], v[198:201], v[82:85]
	v_mfma_f32_16x16x32_bf16 v[74:77], v[174:177], v[198:201], v[74:77]
	v_mfma_f32_16x16x32_bf16 v[70:73], v[166:169], v[206:209], v[70:73]
	v_mfma_f32_16x16x32_bf16 v[66:69], v[174:177], v[206:209], v[66:69]
	s_setprio 0
	s_barrier
	s_add_i32 s62, s63, s26
	s_mov_b32 m0, s62
	ds_read_b128 v[178:181], v145 offset:16384
	ds_read_b128 v[182:185], v145 offset:17408
	ds_read_b128 v[186:189], v145 offset:18432
	ds_read_b128 v[190:193], v145 offset:19456
	ds_read_b128 v[194:197], v145 offset:20480
	ds_read_b128 v[198:201], v145 offset:21504
	ds_read_b128 v[202:205], v145 offset:22528
	ds_read_b128 v[206:209], v145 offset:23552
	global_load_lds_dwordx4 v0, s[70:71]
	s_add_i32 m0, s62, 0x2000
	s_add_u32 s62, s70, 0x40000
	s_addc_u32 s63, s71, 0
	s_add_i32 s61, s61, s26
	global_load_lds_dwordx4 v134, s[70:71]
	s_mov_b32 m0, s61
	s_nop 0
	global_load_lds_dwordx4 v0, s[62:63]
	s_add_i32 m0, s61, 0x2000
	s_nop 0
	global_load_lds_dwordx4 v134, s[62:63]
	s_mov_b32 m0, s17
	s_nop 0
	global_load_lds_dwordx4 v130, s[72:73]
	s_mov_b32 m0, s27
	s_nop 0
	global_load_lds_dwordx4 v132, s[72:73]
	s_cmp_lg_u32 s60, -2
	s_cbranch_scc1 .Lra_n_o2
	s_cmp_lt_u32 s37, 2
	s_cbranch_scc1 .Lra_n_o2
	s_waitcnt vmcnt(24)
	s_branch .Lra_d_o2

; #define PG8_STAGE(bufoff, gbase, voff) do { _Pragma("unroll") for (int _i = 0; _i < 2; ++_i) \
;         __builtin_amdgcn_global_load_lds((const unsigned*)((const char*)(gbase) + (voff)[_i]), (PG8_LAS unsigned*)(lds + (bufoff) + ldsw + _i * 8192), 16, 0, 0); } while (0)
; #define PG8_LDA(dst, b, h) do { _Pragma("unroll") for (int m = 0; m < 4; ++m) _Pragma("unroll") for (int k = 0; k < 2; ++k) dst[m][k] = *(const PG8_LAS bf16x8*)(lds + PG8_SA(b, h) + aoff + m * 2048 + k * 1024); } while (0)
; #define PG8_LDB(dst, b, h) do { _Pragma("unroll") for (int n = 0; n < 2; ++n) _Pragma("unroll") for (int k = 0; k < 2; ++k) dst[n][k] = *(const PG8_LAS bf16x8*)(lds + PG8_SB(b, h) + boff + n * 2048 + k * 1024); } while (0)
; #define PG8_MMA(ai, bj, At, Bt) do { __builtin_amdgcn_s_setprio(1); _Pragma("unroll") for (int m = 0; m < 4; ++m) _Pragma("unroll") for (int n = 0; n < 2; ++n) _Pragma("unroll") for (int k = 0; k < 2; ++k) \
;         acc[ai][bj][m][n] = __builtin_amdgcn_mfma_f32_16x16x32_bf16(Bt[n][k], At[m][k], acc[ai][bj][m][n], 0, 0, 0); __builtin_amdgcn_s_setprio(0); } while (0)
; #define PG8_BAR __builtin_amdgcn_s_barrier()
; template <class Epi, class Sched, bool ALIGN_EPI = false, bool SP2 = false>
; __device__ __forceinline__ void gemm_phase(PG8_LAS unsigned char* lds, const Gemm g, const Sched& S, const Epi& E, const int tid_in) {
;     ...
;             PG8_LDB(B0, 0, 0); PG8_LDB(B1, 0, 1); PG8_SCHED; PG8_LDA(At, 0, 0); PG8_STAGE(PG8_SA(1, 1), a1 + hstep, voffA);
;             PG8_WAIT_V(8); PG8_WAIT_L(0); PG8_BAR; PG8_MMA(0, 0, At, B0); PG8_MMA(0, 1, At, B1); PG8_BAR; PG8_SCHED;
;             PG8_LDA(At, 0, 1); PG8_STAGE(PG8_SB(0, 0), b2, voffB); PG8_STAGE(PG8_SB(0, 1), b2 + hstep, voffB); PG8_STAGE(PG8_SA(0, 0), a2, voffA);
;             PG8_WAIT_V(8); PG8_WAIT_L(0); PG8_BAR; PG8_MMA(1, 0, At, B0); PG8_MMA(1, 1, At, B1); PG8_BAR; PG8_SCHED;
;             PG8_LDB(B0, 1, 0); PG8_LDB(B1, 1, 1); PG8_SCHED; PG8_LDA(At, 1, 0); PG8_STAGE(PG8_SA(0, 1), a2 + hstep, voffA);
;             PG8_WAIT_V(8); PG8_WAIT_L(0); PG8_BAR; PG8_MMA(0, 0, At, B0); PG8_MMA(0, 1, At, B1); PG8_BAR; PG8_SCHED;
;             PG8_LDA(At, 1, 1); PG8_STAGE(PG8_SB(1, 0), b3, voffB); PG8_STAGE(PG8_SB(1, 1), b3 + hstep, voffB); PG8_STAGE(PG8_SA(1, 0), a3, voffA);
;             PG8_WAIT_V(8); PG8_WAIT_L(0); PG8_BAR; PG8_MMA(1, 0, At, B0); PG8_MMA(1, 1, At, B1); PG8_BAR; PG8_SCHED;
.Lra_d_o2:
	s_waitcnt lgkmcnt(0)
	s_barrier
	s_setprio 1
	s_waitcnt lgkmcnt(0)
	v_mfma_f32_16x16x32_bf16 v[62:65], v[146:149], v[178:181], v[62:65]
	v_mfma_f32_16x16x32_bf16 v[58:61], v[154:157], v[178:181], v[58:61]
	v_mfma_f32_16x16x32_bf16 v[54:57], v[146:149], v[186:189], v[54:57]
	v_mfma_f32_16x16x32_bf16 v[46:49], v[154:157], v[186:189], v[46:49]
	v_mfma_f32_16x16x32_bf16 v[38:41], v[146:149], v[194:197], v[38:41]
	v_mfma_f32_16x16x32_bf16 v[30:33], v[154:157], v[194:197], v[30:33]
	v_mfma_f32_16x16x32_bf16 v[22:25], v[146:149], v[202:205], v[22:25]
	v_mfma_f32_16x16x32_bf16 v[14:17], v[154:157], v[202:205], v[14:17]
	v_mfma_f32_16x16x32_bf16 v[62:65], v[150:153], v[182:185], v[62:65]
	v_mfma_f32_16x16x32_bf16 v[58:61], v[158:161], v[182:185], v[58:61]
	v_mfma_f32_16x16x32_bf16 v[54:57], v[150:153], v[190:193], v[54:57]
	v_mfma_f32_16x16x32_bf16 v[46:49], v[158:161], v[190:193], v[46:49]
	v_mfma_f32_16x16x32_bf16 v[38:41], v[150:153], v[198:201], v[38:41]
	v_mfma_f32_16x16x32_bf16 v[30:33], v[158:161], v[198:201], v[30:33]
	v_mfma_f32_16x16x32_bf16 v[22:25], v[150:153], v[206:209], v[22:25]
	v_mfma_f32_16x16x32_bf16 v[14:17], v[158:161], v[206:209], v[14:17]
	s_setprio 0
	s_setprio 1
	v_mfma_f32_16x16x32_bf16 v[50:53], v[162:165], v[178:181], v[50:53]
	v_mfma_f32_16x16x32_bf16 v[42:45], v[170:173], v[178:181], v[42:45]
	v_mfma_f32_16x16x32_bf16 v[34:37], v[162:165], v[186:189], v[34:37]
	v_mfma_f32_16x16x32_bf16 v[26:29], v[170:173], v[186:189], v[26:29]
	v_mfma_f32_16x16x32_bf16 v[18:21], v[162:165], v[194:197], v[18:21]
	v_mfma_f32_16x16x32_bf16 v[10:13], v[170:173], v[194:197], v[10:13]
	v_mfma_f32_16x16x32_bf16 v[6:9], v[162:165], v[202:205], v[6:9]
	v_mfma_f32_16x16x32_bf16 v[2:5], v[170:173], v[202:205], v[2:5]
	v_mfma_f32_16x16x32_bf16 v[50:53], v[166:169], v[182:185], v[50:53]
	v_mfma_f32_16x16x32_bf16 v[42:45], v[174:177], v[182:185], v[42:45]
	v_mfma_f32_16x16x32_bf16 v[34:37], v[166:169], v[190:193], v[34:37]
	v_mfma_f32_16x16x32_bf16 v[26:29], v[174:177], v[190:193], v[26:29]
	v_mfma_f32_16x16x32_bf16 v[18:21], v[166:169], v[198:201], v[18:21]
	v_mfma_f32_16x16x32_bf16 v[10:13], v[174:177], v[198:201], v[10:13]
	v_mfma_f32_16x16x32_bf16 v[6:9], v[166:169], v[206:209], v[6:9]
	v_mfma_f32_16x16x32_bf16 v[2:5], v[174:177], v[206:209], v[2:5]
	s_setprio 0
	s_barrier
	s_add_i32 s61, 0, 0x18000
	s_add_i32 s64, 0, 0x1c000
	v_add_u32_e32 v158, s61, v143
	v_add_u32_e32 v174, s64, v143
	ds_read_b128 v[146:149], v158
	ds_read_b128 v[150:153], v158 offset:1024
	ds_read_b128 v[154:157], v158 offset:2048
	ds_read_b128 v[158:161], v158 offset:3072
	ds_read_b128 v[162:165], v174
	ds_read_b128 v[166:169], v174 offset:1024
	ds_read_b128 v[170:173], v174 offset:2048
	ds_read_b128 v[174:177], v174 offset:3072
	s_add_u32 s62, s72, 0x40000
	s_addc_u32 s63, s73, 0
	s_mov_b32 m0, s29
	ds_read_b128 v[178:181], v145 offset:32768
	ds_read_b128 v[182:185], v145 offset:33792
	ds_read_b128 v[186:189], v145 offset:34816
	ds_read_b128 v[190:193], v145 offset:35840
	ds_read_b128 v[194:197], v145 offset:36864
	ds_read_b128 v[198:201], v145 offset:37888
	ds_read_b128 v[202:205], v145 offset:38912
	ds_read_b128 v[206:209], v145 offset:39936
	global_load_lds_dwordx4 v130, s[62:63]
	s_mov_b32 m0, s34
	s_nop 0
	global_load_lds_dwordx4 v132, s[62:63]
	s_waitcnt vmcnt(8)
	s_waitcnt lgkmcnt(0)
	s_barrier
	s_setprio 1
	s_waitcnt lgkmcnt(0)
	v_mfma_f32_16x16x32_bf16 v[126:129], v[146:149], v[178:181], v[126:129]
	v_mfma_f32_16x16x32_bf16 v[122:125], v[154:157], v[178:181], v[122:125]
	v_mfma_f32_16x16x32_bf16 v[118:121], v[146:149], v[186:189], v[118:121]
	v_mfma_f32_16x16x32_bf16 v[110:113], v[154:157], v[186:189], v[110:113]
	v_mfma_f32_16x16x32_bf16 v[102:105], v[146:149], v[194:197], v[102:105]
	v_mfma_f32_16x16x32_bf16 v[94:97], v[154:157], v[194:197], v[94:97]
	v_mfma_f32_16x16x32_bf16 v[86:89], v[146:149], v[202:205], v[86:89]
	v_mfma_f32_16x16x32_bf16 v[78:81], v[154:157], v[202:205], v[78:81]
	v_mfma_f32_16x16x32_bf16 v[126:129], v[150:153], v[182:185], v[126:129]
	v_mfma_f32_16x16x32_bf16 v[122:125], v[158:161], v[182:185], v[122:125]
	v_mfma_f32_16x16x32_bf16 v[118:121], v[150:153], v[190:193], v[118:121]
	v_mfma_f32_16x16x32_bf16 v[110:113], v[158:161], v[190:193], v[110:113]
	v_mfma_f32_16x16x32_bf16 v[102:105], v[150:153], v[198:201], v[102:105]
	v_mfma_f32_16x16x32_bf16 v[94:97], v[158:161], v[198:201], v[94:97]
	v_mfma_f32_16x16x32_bf16 v[86:89], v[150:153], v[206:209], v[86:89]
	v_mfma_f32_16x16x32_bf16 v[78:81], v[158:161], v[206:209], v[78:81]
	s_setprio 0
	s_setprio 1
	v_mfma_f32_16x16x32_bf16 v[114:117], v[162:165], v[178:181], v[114:117]
	v_mfma_f32_16x16x32_bf16 v[106:109], v[170:173], v[178:181], v[106:109]
	v_mfma_f32_16x16x32_bf16 v[98:101], v[162:165], v[186:189], v[98:101]
	v_mfma_f32_16x16x32_bf16 v[90:93], v[170:173], v[186:189], v[90:93]
	v_mfma_f32_16x16x32_bf16 v[82:85], v[162:165], v[194:197], v[82:85]
	v_mfma_f32_16x16x32_bf16 v[74:77], v[170:173], v[194:197], v[74:77]
	v_mfma_f32_16x16x32_bf16 v[70:73], v[162:165], v[202:205], v[70:73]
	v_mfma_f32_16x16x32_bf16 v[66:69], v[170:173], v[202:205], v[66:69]
	v_mfma_f32_16x16x32_bf16 v[114:117], v[166:169], v[182:185], v[114:117]
	v_mfma_f32_16x16x32_bf16 v[106:109], v[174:177], v[182:185], v[106:109]
	v_mfma_f32_16x16x32_bf16 v[98:101], v[166:169], v[190:193], v[98:101]
	v_mfma_f32_16x16x32_bf16 v[90:93], v[174:177], v[190:193], v[90:93]
	v_mfma_f32_16x16x32_bf16 v[82:85], v[166:169], v[198:201], v[82:85]
	v_mfma_f32_16x16x32_bf16 v[74:77], v[174:177], v[198:201], v[74:77]
	v_mfma_f32_16x16x32_bf16 v[70:73], v[166:169], v[206:209], v[70:73]
	v_mfma_f32_16x16x32_bf16 v[66:69], v[174:177], v[206:209], v[66:69]
	s_setprio 0
	s_barrier
; #define PG8_STAGE(bufoff, gbase, voff) do { _Pragma("unroll") for (int _i = 0; _i < 2; ++_i) \
;         __builtin_amdgcn_global_load_lds((const unsigned*)((const char*)(gbase) + (voff)[_i]), (PG8_LAS unsigned*)(lds + (bufoff) + ldsw + _i * 8192), 16, 0, 0); } while (0)
; #define PG8_LDA(dst, b, h) do { _Pragma("unroll") for (int m = 0; m < 4; ++m) _Pragma("unroll") for (int k = 0; k < 2; ++k) dst[m][k] = *(const PG8_LAS bf16x8*)(lds + PG8_SA(b, h) + aoff + m * 2048 + k * 1024); } while (0)
; #define PG8_MMA(ai, bj, At, Bt) do { __builtin_amdgcn_s_setprio(1); _Pragma("unroll") for (int m = 0; m < 4; ++m) _Pragma("unroll") for (int n = 0; n < 2; ++n) _Pragma("unroll") for (int k = 0; k < 2; ++k) \
;         acc[ai][bj][m][n] = __builtin_amdgcn_mfma_f32_16x16x32_bf16(Bt[n][k], At[m][k], acc[ai][bj][m][n], 0, 0, 0); __builtin_amdgcn_s_setprio(0); } while (0)
; #define PG8_WAIT_V(n) asm volatile("s_waitcnt vmcnt(" #n ")" ::: "memory")
; #define PG8_WAIT_L(n) asm volatile("s_waitcnt lgkmcnt(" #n ")" ::: "memory")
; #define PG8_BAR __builtin_amdgcn_s_barrier()
; #define PG8_SCHED __builtin_amdgcn_sched_barrier(0)
; template <class Epi, class Sched, bool ALIGN_EPI = false, bool SP2 = false>
; __device__ __forceinline__ void gemm_phase(PG8_LAS unsigned char* lds, const Gemm g, const Sched& S, const Epi& E, const int tid_in) {
;     ...
;             PG8_LDA(At, 1, 1); PG8_STAGE(PG8_SB(1, 0), b3, voffB); PG8_STAGE(PG8_SB(1, 1), b3 + hstep, voffB); PG8_STAGE(PG8_SA(1, 0), a3, voffA);
;             PG8_WAIT_V(8); PG8_WAIT_L(0); PG8_BAR; PG8_MMA(1, 0, At, B0); PG8_MMA(1, 1, At, B1); PG8_BAR; PG8_SCHED;
	s_add_i32 s61, s61, s26
	s_mov_b32 m0, s61
	ds_read_b128 v[178:181], v145 offset:49152
	ds_read_b128 v[182:185], v145 offset:50176
	ds_read_b128 v[186:189], v145 offset:51200
	ds_read_b128 v[190:193], v145 offset:52224
	ds_read_b128 v[194:197], v145 offset:53248
	ds_read_b128 v[198:201], v145 offset:54272
	ds_read_b128 v[202:205], v145 offset:55296
	ds_read_b128 v[206:209], v145 offset:56320
	s_add_u32 s44, s70, 0x80
	s_addc_u32 s45, s71, 0
	global_load_lds_dwordx4 v0, s[44:45]
	s_add_i32 m0, s61, 0x2000
	s_add_u32 s62, s70, 0x40080
	s_addc_u32 s63, s71, 0
	s_add_i32 s61, s64, s26
	global_load_lds_dwordx4 v134, s[44:45]
	s_mov_b32 m0, s61
	s_nop 0
	global_load_lds_dwordx4 v0, s[62:63]
	s_add_i32 m0, s61, 0x2000
	s_nop 0
	global_load_lds_dwordx4 v134, s[62:63]
	s_mov_b32 m0, s35
	s_nop 0
	s_add_u32 s44, s72, 0x80
	s_addc_u32 s45, s73, 0
	global_load_lds_dwordx4 v130, s[44:45]
	s_mov_b32 m0, s36
	s_nop 0
	global_load_lds_dwordx4 v132, s[44:45]
	s_waitcnt vmcnt(8)
	s_waitcnt lgkmcnt(0)
	s_barrier
	s_setprio 1
	s_waitcnt lgkmcnt(0)
	v_mfma_f32_16x16x32_bf16 v[62:65], v[146:149], v[178:181], v[62:65]
	v_mfma_f32_16x16x32_bf16 v[58:61], v[154:157], v[178:181], v[58:61]
	v_mfma_f32_16x16x32_bf16 v[54:57], v[146:149], v[186:189], v[54:57]
	v_mfma_f32_16x16x32_bf16 v[46:49], v[154:157], v[186:189], v[46:49]
	v_mfma_f32_16x16x32_bf16 v[38:41], v[146:149], v[194:197], v[38:41]
	v_mfma_f32_16x16x32_bf16 v[30:33], v[154:157], v[194:197], v[30:33]
	v_mfma_f32_16x16x32_bf16 v[22:25], v[146:149], v[202:205], v[22:25]
	v_mfma_f32_16x16x32_bf16 v[14:17], v[154:157], v[202:205], v[14:17]
	v_mfma_f32_16x16x32_bf16 v[62:65], v[150:153], v[182:185], v[62:65]
	v_mfma_f32_16x16x32_bf16 v[58:61], v[158:161], v[182:185], v[58:61]
	v_mfma_f32_16x16x32_bf16 v[54:57], v[150:153], v[190:193], v[54:57]
	v_mfma_f32_16x16x32_bf16 v[46:49], v[158:161], v[190:193], v[46:49]
	v_mfma_f32_16x16x32_bf16 v[38:41], v[150:153], v[198:201], v[38:41]
	v_mfma_f32_16x16x32_bf16 v[30:33], v[158:161], v[198:201], v[30:33]
	v_mfma_f32_16x16x32_bf16 v[22:25], v[150:153], v[206:209], v[22:25]
	v_mfma_f32_16x16x32_bf16 v[14:17], v[158:161], v[206:209], v[14:17]
	s_setprio 0
	s_setprio 1
	v_mfma_f32_16x16x32_bf16 v[50:53], v[162:165], v[178:181], v[50:53]
	v_mfma_f32_16x16x32_bf16 v[42:45], v[170:173], v[178:181], v[42:45]
	v_mfma_f32_16x16x32_bf16 v[34:37], v[162:165], v[186:189], v[34:37]
	v_mfma_f32_16x16x32_bf16 v[26:29], v[170:173], v[186:189], v[26:29]
	v_mfma_f32_16x16x32_bf16 v[18:21], v[162:165], v[194:197], v[18:21]
	v_mfma_f32_16x16x32_bf16 v[10:13], v[170:173], v[194:197], v[10:13]
	v_mfma_f32_16x16x32_bf16 v[6:9], v[162:165], v[202:205], v[6:9]
	v_mfma_f32_16x16x32_bf16 v[2:5], v[170:173], v[202:205], v[2:5]
	v_mfma_f32_16x16x32_bf16 v[50:53], v[166:169], v[182:185], v[50:53]
	v_mfma_f32_16x16x32_bf16 v[42:45], v[174:177], v[182:185], v[42:45]
	v_mfma_f32_16x16x32_bf16 v[34:37], v[166:169], v[190:193], v[34:37]
	v_mfma_f32_16x16x32_bf16 v[26:29], v[174:177], v[190:193], v[26:29]
	v_mfma_f32_16x16x32_bf16 v[18:21], v[166:169], v[198:201], v[18:21]
	v_mfma_f32_16x16x32_bf16 v[10:13], v[174:177], v[198:201], v[10:13]
	v_mfma_f32_16x16x32_bf16 v[6:9], v[166:169], v[206:209], v[6:9]
	v_mfma_f32_16x16x32_bf16 v[2:5], v[174:177], v[206:209], v[2:5]
	s_setprio 0
	s_barrier
	s_add_i32 s60, s60, 2
	s_add_u32 s68, s68, 0x100
	s_addc_u32 s69, s69, 0
	s_add_u32 s58, s58, 0x100
	s_addc_u32 s59, s59, 0
	s_cmp_gt_u32 s60, 13
	s_cbranch_scc0 .LBB0_485
	s_mov_b64 s[44:45], 0x80
	s_and_b64 vcc, exec, s[10:11]
	s_cbranch_vccz .LBB0_488
	s_barrier

; #define PG8_STAGE(bufoff, gbase, voff) do { _Pragma("unroll") for (int _i = 0; _i < 2; ++_i) \
;         __builtin_amdgcn_global_load_lds((const unsigned*)((const char*)(gbase) + (voff)[_i]), (PG8_LAS unsigned*)(lds + (bufoff) + ldsw + _i * 8192), 16, 0, 0); } while (0)
; #define PG8_LDA(dst, b, h) do { _Pragma("unroll") for (int m = 0; m < 4; ++m) _Pragma("unroll") for (int k = 0; k < 2; ++k) dst[m][k] = *(const PG8_LAS bf16x8*)(lds + PG8_SA(b, h) + aoff + m * 2048 + k * 1024); } while (0)
; #define PG8_LDB(dst, b, h) do { _Pragma("unroll") for (int n = 0; n < 2; ++n) _Pragma("unroll") for (int k = 0; k < 2; ++k) dst[n][k] = *(const PG8_LAS bf16x8*)(lds + PG8_SB(b, h) + boff + n * 2048 + k * 1024); } while (0)
; #define PG8_SCHED __builtin_amdgcn_sched_barrier(0)
; template <class Epi, class Sched, bool ALIGN_EPI = false, bool SP2 = false>
; __device__ __forceinline__ void gemm_phase(PG8_LAS unsigned char* lds, const Gemm g, const Sched& S, const Epi& E, const int tid_in) {
;     ...
;         float rsv[8]; E.pre(cur, wr, fr, rsv);
;         const bool has_next = S.next(ui + 1, nxt);
;         const char* nA = has_next ? (const char*)g.A + (size_t)nxt.pm * tstep : cA; const char* nB = has_next ? (const char*)g.Bt + (size_t)nxt.pn * tstep : cB;
;         for (int t = 0; t < nt; t += 2) {
;             const bool last = (t == nt - 2);
;             const char* a1 = cA + (size_t)(t + 1) * kstep;
;             const char* a2 = last ? nA : cA + (size_t)(t + 2) * kstep; const char* b2 = last ? nB : cB + (size_t)(t + 2) * kstep;
;             const char* a3 = a2 + kstep; const char* b3 = b2 + kstep;
;             if (last && has_next) S.a_ready(nxt);
;             if constexpr (SP2) {
;             PG8_LDB(B0, 0, 0); PG8_LDB(B1, 0, 1); PG8_SCHED; PG8_LDA(At, 0, 0); PG8_STAGE(PG8_SA(1, 1), a1 + hstep, voffA);
;     ...
;         for (int a = 0; a < 2; ++a)
; #pragma unroll
;             for (int b = 0; b < 2; ++b)
; #pragma unroll
;                 for (int m = 0; m < 4; ++m)
; #pragma unroll
;                     for (int n = 0; n < 2; ++n) acc[a][b][m][n] = (f32x4){0.f, 0.f, 0.f, 0.f};
.LBB0_621:
	s_ashr_i32 s7, s6, 31
	s_lshl_b64 s[22:23], s[6:7], 19
	s_add_u32 s22, s1, s22
	s_addc_u32 s23, s2, s23
	s_and_b64 s[58:59], s[4:5], exec
	s_cselect_b32 s7, s23, s71
	s_cselect_b32 s43, s22, s70
	s_ashr_i32 s19, s18, 31
	s_lshl_b64 s[58:59], s[18:19], 19
	s_add_u32 s68, s3, s58
	s_addc_u32 s69, s20, s59
	s_and_b64 s[58:59], s[4:5], exec
	s_cselect_b32 s19, s69, s73
	s_cselect_b32 s58, s68, s72
	s_add_u32 s70, s70, 0x40080
	s_addc_u32 s71, s71, 0
	s_add_u32 s59, s72, 0x100
	v_mov_b32_e32 v2, 0
	s_addc_u32 s60, s73, 0
	s_mov_b32 s61, -2
	v_mov_b32_e32 v3, v2
	v_mov_b64_e32 v[4:5], 0
	v_mov_b64_e32 v[10:11], 0
	v_mov_b64_e32 v[12:13], 0
	v_mov_b64_e32 v[18:19], 0
	v_mov_b64_e32 v[20:21], 0
	v_mov_b64_e32 v[26:27], 0
	v_mov_b64_e32 v[28:29], 0
	v_mov_b64_e32 v[34:35], 0
	v_mov_b64_e32 v[36:37], 0
	v_mov_b64_e32 v[42:43], 0
	v_mov_b64_e32 v[44:45], 0
	v_mov_b64_e32 v[50:51], 0
	v_mov_b64_e32 v[52:53], 0
	v_mov_b64_e32 v[58:59], 0
	v_mov_b64_e32 v[60:61], 0
	v_mov_b64_e32 v[6:7], 0
	v_mov_b64_e32 v[8:9], 0
	v_mov_b64_e32 v[14:15], 0
	v_mov_b64_e32 v[16:17], 0
	v_mov_b64_e32 v[22:23], 0
	v_mov_b64_e32 v[24:25], 0
	v_mov_b64_e32 v[30:31], 0
	v_mov_b64_e32 v[32:33], 0
	v_mov_b64_e32 v[38:39], 0
	v_mov_b64_e32 v[40:41], 0
	v_mov_b64_e32 v[46:47], 0
	v_mov_b64_e32 v[48:49], 0
	v_mov_b64_e32 v[54:55], 0
	v_mov_b64_e32 v[56:57], 0
	v_mov_b64_e32 v[62:63], 0
	v_mov_b64_e32 v[64:65], 0
	v_mov_b64_e32 v[66:67], 0
	v_mov_b64_e32 v[68:69], 0
	v_mov_b64_e32 v[74:75], 0
	v_mov_b64_e32 v[76:77], 0
	v_mov_b64_e32 v[82:83], 0
	v_mov_b64_e32 v[84:85], 0
	v_mov_b64_e32 v[90:91], 0
	v_mov_b64_e32 v[92:93], 0
	v_mov_b64_e32 v[98:99], 0
	v_mov_b64_e32 v[100:101], 0
	v_mov_b64_e32 v[106:107], 0
	v_mov_b64_e32 v[108:109], 0
	v_mov_b64_e32 v[114:115], 0
	v_mov_b64_e32 v[116:117], 0
	v_mov_b64_e32 v[122:123], 0
	v_mov_b64_e32 v[124:125], 0
	v_mov_b64_e32 v[70:71], 0
	v_mov_b64_e32 v[72:73], 0
	v_mov_b64_e32 v[78:79], 0
	v_mov_b64_e32 v[80:81], 0
	v_mov_b64_e32 v[86:87], 0
	v_mov_b64_e32 v[88:89], 0
	v_mov_b64_e32 v[94:95], 0
	v_mov_b64_e32 v[96:97], 0
	v_mov_b64_e32 v[102:103], 0
	v_mov_b64_e32 v[104:105], 0
	v_mov_b64_e32 v[110:111], 0
	v_mov_b64_e32 v[112:113], 0
	v_mov_b64_e32 v[118:119], 0
	v_mov_b64_e32 v[120:121], 0
	v_mov_b64_e32 v[126:127], 0
	v_mov_b64_e32 v[128:129], 0
.LBB0_622:
	s_add_u32 s62, s70, 0xfffc0080
	s_addc_u32 s63, s71, -1
	s_add_i32 s64, 0, 0x10000
	s_cmp_eq_u32 s61, 12
	s_cselect_b32 s75, s7, s63
	s_cselect_b32 s74, s43, s62
	v_add_u32_e32 v143, s64, v145
	s_cselect_b32 s73, s19, s60
	s_cselect_b32 s72, s58, s59
	s_add_i32 s76, 0, 0x14000
	ds_read_b128 v[160:163], v143
	ds_read_b128 v[164:167], v143 offset:1024
	ds_read_b128 v[168:171], v143 offset:2048
	ds_read_b128 v[172:175], v143 offset:3072
	v_add_u32_e32 v143, s76, v145
	ds_read_b128 v[176:179], v143
	ds_read_b128 v[180:183], v143 offset:1024
	ds_read_b128 v[184:187], v143 offset:2048
	ds_read_b128 v[188:191], v143 offset:3072
	s_add_i32 m0, s27, 0xc000
	ds_read_b128 v[192:195], v149
	ds_read_b128 v[196:199], v149 offset:1024
	ds_read_b128 v[200:203], v149 offset:2048
	ds_read_b128 v[204:207], v149 offset:3072
	ds_read_b128 v[208:211], v149 offset:4096
	ds_read_b128 v[212:215], v149 offset:5120
	ds_read_b128 v[216:219], v149 offset:6144
	ds_read_b128 v[220:223], v149 offset:7168
	global_load_lds_dwordx4 v136, s[70:71]
	s_add_i32 m0, s27, 0xe000
	s_nop 0
	global_load_lds_dwordx4 v138, s[70:71]
	s_cmp_lg_u32 s61, -2
	s_cbranch_scc1 .Lra_n_f1
	s_cmp_lt_u32 s38, 2
	s_cbranch_scc1 .Lra_n_f1
	s_waitcnt vmcnt(24)
	s_branch .Lra_d_f1

; #define PG8_STAGE(bufoff, gbase, voff) do { _Pragma("unroll") for (int _i = 0; _i < 2; ++_i) \
;         __builtin_amdgcn_global_load_lds((const unsigned*)((const char*)(gbase) + (voff)[_i]), (PG8_LAS unsigned*)(lds + (bufoff) + ldsw + _i * 8192), 16, 0, 0); } while (0)
; #define PG8_LDA(dst, b, h) do { _Pragma("unroll") for (int m = 0; m < 4; ++m) _Pragma("unroll") for (int k = 0; k < 2; ++k) dst[m][k] = *(const PG8_LAS bf16x8*)(lds + PG8_SA(b, h) + aoff + m * 2048 + k * 1024); } while (0)
; #define PG8_MMA(ai, bj, At, Bt) do { __builtin_amdgcn_s_setprio(1); _Pragma("unroll") for (int m = 0; m < 4; ++m) _Pragma("unroll") for (int n = 0; n < 2; ++n) _Pragma("unroll") for (int k = 0; k < 2; ++k) \
;         acc[ai][bj][m][n] = __builtin_amdgcn_mfma_f32_16x16x32_bf16(Bt[n][k], At[m][k], acc[ai][bj][m][n], 0, 0, 0); __builtin_amdgcn_s_setprio(0); } while (0)
; #define PG8_WAIT_V(n) asm volatile("s_waitcnt vmcnt(" #n ")" ::: "memory")
; #define PG8_WAIT_L(n) asm volatile("s_waitcnt lgkmcnt(" #n ")" ::: "memory")
; #define PG8_BAR __builtin_amdgcn_s_barrier()
; #define PG8_SCHED __builtin_amdgcn_sched_barrier(0)
; template <class Epi, class Sched, bool ALIGN_EPI = false, bool SP2 = false>
; __device__ __forceinline__ void gemm_phase(PG8_LAS unsigned char* lds, const Gemm g, const Sched& S, const Epi& E, const int tid_in) {
;     ...
;             PG8_WAIT_V(8); PG8_WAIT_L(0); PG8_BAR; PG8_MMA(0, 0, At, B0); PG8_MMA(0, 1, At, B1); PG8_BAR; PG8_SCHED;
;             PG8_LDA(At, 0, 1); PG8_STAGE(PG8_SB(0, 0), b2, voffB); PG8_STAGE(PG8_SB(0, 1), b2 + hstep, voffB); PG8_STAGE(PG8_SA(0, 0), a2, voffA);
;             PG8_WAIT_V(8); PG8_WAIT_L(0); PG8_BAR; PG8_MMA(1, 0, At, B0); PG8_MMA(1, 1, At, B1); PG8_BAR; PG8_SCHED;
.Lra_d_f1:
	s_waitcnt lgkmcnt(0)
	s_barrier
	s_setprio 1
	s_waitcnt lgkmcnt(0)
	v_mfma_f32_16x16x32_bf16 v[126:129], v[160:163], v[192:195], v[126:129]
	v_mfma_f32_16x16x32_bf16 v[118:121], v[168:171], v[192:195], v[118:121]
	v_mfma_f32_16x16x32_bf16 v[110:113], v[160:163], v[200:203], v[110:113]
	v_mfma_f32_16x16x32_bf16 v[102:105], v[168:171], v[200:203], v[102:105]
	v_mfma_f32_16x16x32_bf16 v[94:97], v[160:163], v[208:211], v[94:97]
	v_mfma_f32_16x16x32_bf16 v[86:89], v[168:171], v[208:211], v[86:89]
	v_mfma_f32_16x16x32_bf16 v[78:81], v[160:163], v[216:219], v[78:81]
	v_mfma_f32_16x16x32_bf16 v[70:73], v[168:171], v[216:219], v[70:73]
	v_mfma_f32_16x16x32_bf16 v[126:129], v[164:167], v[196:199], v[126:129]
	v_mfma_f32_16x16x32_bf16 v[118:121], v[172:175], v[196:199], v[118:121]
	v_mfma_f32_16x16x32_bf16 v[110:113], v[164:167], v[204:207], v[110:113]
	v_mfma_f32_16x16x32_bf16 v[102:105], v[172:175], v[204:207], v[102:105]
	v_mfma_f32_16x16x32_bf16 v[94:97], v[164:167], v[212:215], v[94:97]
	v_mfma_f32_16x16x32_bf16 v[86:89], v[172:175], v[212:215], v[86:89]
	v_mfma_f32_16x16x32_bf16 v[78:81], v[164:167], v[220:223], v[78:81]
	v_mfma_f32_16x16x32_bf16 v[70:73], v[172:175], v[220:223], v[70:73]
	s_setprio 0
	s_setprio 1
	v_mfma_f32_16x16x32_bf16 v[122:125], v[176:179], v[192:195], v[122:125]
	v_mfma_f32_16x16x32_bf16 v[114:117], v[184:187], v[192:195], v[114:117]
	v_mfma_f32_16x16x32_bf16 v[106:109], v[176:179], v[200:203], v[106:109]
	v_mfma_f32_16x16x32_bf16 v[98:101], v[184:187], v[200:203], v[98:101]
	v_mfma_f32_16x16x32_bf16 v[90:93], v[176:179], v[208:211], v[90:93]
	v_mfma_f32_16x16x32_bf16 v[82:85], v[184:187], v[208:211], v[82:85]
	v_mfma_f32_16x16x32_bf16 v[74:77], v[176:179], v[216:219], v[74:77]
	v_mfma_f32_16x16x32_bf16 v[66:69], v[184:187], v[216:219], v[66:69]
	v_mfma_f32_16x16x32_bf16 v[122:125], v[180:183], v[196:199], v[122:125]
	v_mfma_f32_16x16x32_bf16 v[114:117], v[188:191], v[196:199], v[114:117]
	v_mfma_f32_16x16x32_bf16 v[106:109], v[180:183], v[204:207], v[106:109]
	v_mfma_f32_16x16x32_bf16 v[98:101], v[188:191], v[204:207], v[98:101]
	v_mfma_f32_16x16x32_bf16 v[90:93], v[180:183], v[212:215], v[90:93]
	v_mfma_f32_16x16x32_bf16 v[82:85], v[188:191], v[212:215], v[82:85]
	v_mfma_f32_16x16x32_bf16 v[74:77], v[180:183], v[220:223], v[74:77]
	v_mfma_f32_16x16x32_bf16 v[66:69], v[188:191], v[220:223], v[66:69]
	s_setprio 0
	s_barrier
	s_add_i32 s62, s64, s21
	s_mov_b32 m0, s62
	ds_read_b128 v[192:195], v149 offset:16384
	ds_read_b128 v[196:199], v149 offset:17408
	ds_read_b128 v[200:203], v149 offset:18432
	ds_read_b128 v[204:207], v149 offset:19456
	ds_read_b128 v[208:211], v149 offset:20480
	ds_read_b128 v[212:215], v149 offset:21504
	ds_read_b128 v[216:219], v149 offset:22528
	ds_read_b128 v[220:223], v149 offset:23552
	global_load_lds_dwordx4 v0, s[72:73]
	s_add_i32 m0, s62, 0x2000
	s_add_u32 s62, s72, 0x40000
	s_addc_u32 s63, s73, 0
	s_add_i32 s64, s76, s21
	global_load_lds_dwordx4 v130, s[72:73]
	s_mov_b32 m0, s64
	s_nop 0
	global_load_lds_dwordx4 v0, s[62:63]
	s_add_i32 m0, s64, 0x2000
	s_nop 0
	global_load_lds_dwordx4 v130, s[62:63]
	s_mov_b32 m0, s27
	s_nop 0
	global_load_lds_dwordx4 v134, s[74:75]
	s_mov_b32 m0, s29
	s_nop 0
	global_load_lds_dwordx4 v132, s[74:75]
	s_cmp_lg_u32 s61, -2
	s_cbranch_scc1 .Lra_n_f2
	s_cmp_lt_u32 s38, 2
	s_cbranch_scc1 .Lra_n_f2
	s_waitcnt vmcnt(24)
	s_branch .Lra_d_f2

; #define PG8_STAGE(bufoff, gbase, voff) do { _Pragma("unroll") for (int _i = 0; _i < 2; ++_i) \
;         __builtin_amdgcn_global_load_lds((const unsigned*)((const char*)(gbase) + (voff)[_i]), (PG8_LAS unsigned*)(lds + (bufoff) + ldsw + _i * 8192), 16, 0, 0); } while (0)
; #define PG8_LDA(dst, b, h) do { _Pragma("unroll") for (int m = 0; m < 4; ++m) _Pragma("unroll") for (int k = 0; k < 2; ++k) dst[m][k] = *(const PG8_LAS bf16x8*)(lds + PG8_SA(b, h) + aoff + m * 2048 + k * 1024); } while (0)
; #define PG8_LDB(dst, b, h) do { _Pragma("unroll") for (int n = 0; n < 2; ++n) _Pragma("unroll") for (int k = 0; k < 2; ++k) dst[n][k] = *(const PG8_LAS bf16x8*)(lds + PG8_SB(b, h) + boff + n * 2048 + k * 1024); } while (0)
; #define PG8_MMA(ai, bj, At, Bt) do { __builtin_amdgcn_s_setprio(1); _Pragma("unroll") for (int m = 0; m < 4; ++m) _Pragma("unroll") for (int n = 0; n < 2; ++n) _Pragma("unroll") for (int k = 0; k < 2; ++k) \
;         acc[ai][bj][m][n] = __builtin_amdgcn_mfma_f32_16x16x32_bf16(Bt[n][k], At[m][k], acc[ai][bj][m][n], 0, 0, 0); __builtin_amdgcn_s_setprio(0); } while (0)
; #define PG8_WAIT_V(n) asm volatile("s_waitcnt vmcnt(" #n ")" ::: "memory")
; #define PG8_WAIT_L(n) asm volatile("s_waitcnt lgkmcnt(" #n ")" ::: "memory")
; #define PG8_BAR __builtin_amdgcn_s_barrier()
; #define PG8_SCHED __builtin_amdgcn_sched_barrier(0)
; template <class Epi, class Sched, bool ALIGN_EPI = false, bool SP2 = false>
; __device__ __forceinline__ void gemm_phase(PG8_LAS unsigned char* lds, const Gemm g, const Sched& S, const Epi& E, const int tid_in) {
;     ...
;             PG8_WAIT_V(8); PG8_WAIT_L(0); PG8_BAR; PG8_MMA(1, 0, At, B0); PG8_MMA(1, 1, At, B1); PG8_BAR; PG8_SCHED;
;             PG8_LDB(B0, 1, 0); PG8_LDB(B1, 1, 1); PG8_SCHED; PG8_LDA(At, 1, 0); PG8_STAGE(PG8_SA(0, 1), a2 + hstep, voffA);
;             PG8_WAIT_V(8); PG8_WAIT_L(0); PG8_BAR; PG8_MMA(0, 0, At, B0); PG8_MMA(0, 1, At, B1); PG8_BAR; PG8_SCHED;
.Lra_d_f2:
	s_waitcnt lgkmcnt(0)
	s_barrier
	s_setprio 1
	s_waitcnt lgkmcnt(0)
	v_mfma_f32_16x16x32_bf16 v[62:65], v[160:163], v[192:195], v[62:65]
	v_mfma_f32_16x16x32_bf16 v[54:57], v[168:171], v[192:195], v[54:57]
	v_mfma_f32_16x16x32_bf16 v[46:49], v[160:163], v[200:203], v[46:49]
	v_mfma_f32_16x16x32_bf16 v[38:41], v[168:171], v[200:203], v[38:41]
	v_mfma_f32_16x16x32_bf16 v[30:33], v[160:163], v[208:211], v[30:33]
	v_mfma_f32_16x16x32_bf16 v[22:25], v[168:171], v[208:211], v[22:25]
	v_mfma_f32_16x16x32_bf16 v[14:17], v[160:163], v[216:219], v[14:17]
	v_mfma_f32_16x16x32_bf16 v[6:9], v[168:171], v[216:219], v[6:9]
	v_mfma_f32_16x16x32_bf16 v[62:65], v[164:167], v[196:199], v[62:65]
	v_mfma_f32_16x16x32_bf16 v[54:57], v[172:175], v[196:199], v[54:57]
	v_mfma_f32_16x16x32_bf16 v[46:49], v[164:167], v[204:207], v[46:49]
	v_mfma_f32_16x16x32_bf16 v[38:41], v[172:175], v[204:207], v[38:41]
	v_mfma_f32_16x16x32_bf16 v[30:33], v[164:167], v[212:215], v[30:33]
	v_mfma_f32_16x16x32_bf16 v[22:25], v[172:175], v[212:215], v[22:25]
	v_mfma_f32_16x16x32_bf16 v[14:17], v[164:167], v[220:223], v[14:17]
	v_mfma_f32_16x16x32_bf16 v[6:9], v[172:175], v[220:223], v[6:9]
	s_setprio 0
	s_setprio 1
	v_mfma_f32_16x16x32_bf16 v[58:61], v[176:179], v[192:195], v[58:61]
	v_mfma_f32_16x16x32_bf16 v[50:53], v[184:187], v[192:195], v[50:53]
	v_mfma_f32_16x16x32_bf16 v[42:45], v[176:179], v[200:203], v[42:45]
	v_mfma_f32_16x16x32_bf16 v[34:37], v[184:187], v[200:203], v[34:37]
	v_mfma_f32_16x16x32_bf16 v[26:29], v[176:179], v[208:211], v[26:29]
	v_mfma_f32_16x16x32_bf16 v[18:21], v[184:187], v[208:211], v[18:21]
	v_mfma_f32_16x16x32_bf16 v[10:13], v[176:179], v[216:219], v[10:13]
	v_mfma_f32_16x16x32_bf16 v[2:5], v[184:187], v[216:219], v[2:5]
	v_mfma_f32_16x16x32_bf16 v[58:61], v[180:183], v[196:199], v[58:61]
	v_mfma_f32_16x16x32_bf16 v[50:53], v[188:191], v[196:199], v[50:53]
	v_mfma_f32_16x16x32_bf16 v[42:45], v[180:183], v[204:207], v[42:45]
	v_mfma_f32_16x16x32_bf16 v[34:37], v[188:191], v[204:207], v[34:37]
	v_mfma_f32_16x16x32_bf16 v[26:29], v[180:183], v[212:215], v[26:29]
	v_mfma_f32_16x16x32_bf16 v[18:21], v[188:191], v[212:215], v[18:21]
	v_mfma_f32_16x16x32_bf16 v[10:13], v[180:183], v[220:223], v[10:13]
	v_mfma_f32_16x16x32_bf16 v[2:5], v[188:191], v[220:223], v[2:5]
	s_setprio 0
	s_barrier
	s_add_i32 s64, 0, 0x18000
	v_add_u32_e32 v143, s64, v145
	s_add_i32 s76, 0, 0x1c000
	ds_read_b128 v[160:163], v143
	ds_read_b128 v[164:167], v143 offset:1024
	ds_read_b128 v[168:171], v143 offset:2048
	ds_read_b128 v[172:175], v143 offset:3072
	v_add_u32_e32 v143, s76, v145
	ds_read_b128 v[176:179], v143
	ds_read_b128 v[180:183], v143 offset:1024
	ds_read_b128 v[184:187], v143 offset:2048
	ds_read_b128 v[188:191], v143 offset:3072
	s_add_u32 s62, s74, 0x40000
	s_addc_u32 s63, s75, 0
	s_mov_b32 m0, s34
	ds_read_b128 v[192:195], v149 offset:32768
	ds_read_b128 v[196:199], v149 offset:33792
	ds_read_b128 v[200:203], v149 offset:34816
	ds_read_b128 v[204:207], v149 offset:35840
	ds_read_b128 v[208:211], v149 offset:36864
	ds_read_b128 v[212:215], v149 offset:37888
	ds_read_b128 v[216:219], v149 offset:38912
	ds_read_b128 v[220:223], v149 offset:39936
	global_load_lds_dwordx4 v134, s[62:63]
	s_mov_b32 m0, s35
	s_nop 0
	global_load_lds_dwordx4 v132, s[62:63]
	s_waitcnt vmcnt(8)
	s_waitcnt lgkmcnt(0)
	s_barrier
	s_setprio 1
	s_waitcnt lgkmcnt(0)
	v_mfma_f32_16x16x32_bf16 v[126:129], v[160:163], v[192:195], v[126:129]
	v_mfma_f32_16x16x32_bf16 v[118:121], v[168:171], v[192:195], v[118:121]
	v_mfma_f32_16x16x32_bf16 v[110:113], v[160:163], v[200:203], v[110:113]
	v_mfma_f32_16x16x32_bf16 v[102:105], v[168:171], v[200:203], v[102:105]
	v_mfma_f32_16x16x32_bf16 v[94:97], v[160:163], v[208:211], v[94:97]
	v_mfma_f32_16x16x32_bf16 v[86:89], v[168:171], v[208:211], v[86:89]
	v_mfma_f32_16x16x32_bf16 v[78:81], v[160:163], v[216:219], v[78:81]
	v_mfma_f32_16x16x32_bf16 v[70:73], v[168:171], v[216:219], v[70:73]
	v_mfma_f32_16x16x32_bf16 v[126:129], v[164:167], v[196:199], v[126:129]
	v_mfma_f32_16x16x32_bf16 v[118:121], v[172:175], v[196:199], v[118:121]
	v_mfma_f32_16x16x32_bf16 v[110:113], v[164:167], v[204:207], v[110:113]
	v_mfma_f32_16x16x32_bf16 v[102:105], v[172:175], v[204:207], v[102:105]
	v_mfma_f32_16x16x32_bf16 v[94:97], v[164:167], v[212:215], v[94:97]
	v_mfma_f32_16x16x32_bf16 v[86:89], v[172:175], v[212:215], v[86:89]
	v_mfma_f32_16x16x32_bf16 v[78:81], v[164:167], v[220:223], v[78:81]
	v_mfma_f32_16x16x32_bf16 v[70:73], v[172:175], v[220:223], v[70:73]
	s_setprio 0
	s_setprio 1
	v_mfma_f32_16x16x32_bf16 v[122:125], v[176:179], v[192:195], v[122:125]
	v_mfma_f32_16x16x32_bf16 v[114:117], v[184:187], v[192:195], v[114:117]
	v_mfma_f32_16x16x32_bf16 v[106:109], v[176:179], v[200:203], v[106:109]
	v_mfma_f32_16x16x32_bf16 v[98:101], v[184:187], v[200:203], v[98:101]
	v_mfma_f32_16x16x32_bf16 v[90:93], v[176:179], v[208:211], v[90:93]
	v_mfma_f32_16x16x32_bf16 v[82:85], v[184:187], v[208:211], v[82:85]
	v_mfma_f32_16x16x32_bf16 v[74:77], v[176:179], v[216:219], v[74:77]
	v_mfma_f32_16x16x32_bf16 v[66:69], v[184:187], v[216:219], v[66:69]
	v_mfma_f32_16x16x32_bf16 v[122:125], v[180:183], v[196:199], v[122:125]
	v_mfma_f32_16x16x32_bf16 v[114:117], v[188:191], v[196:199], v[114:117]
	v_mfma_f32_16x16x32_bf16 v[106:109], v[180:183], v[204:207], v[106:109]
	v_mfma_f32_16x16x32_bf16 v[98:101], v[188:191], v[204:207], v[98:101]
	v_mfma_f32_16x16x32_bf16 v[90:93], v[180:183], v[212:215], v[90:93]
	v_mfma_f32_16x16x32_bf16 v[82:85], v[188:191], v[212:215], v[82:85]
	v_mfma_f32_16x16x32_bf16 v[74:77], v[180:183], v[220:223], v[74:77]
	v_mfma_f32_16x16x32_bf16 v[66:69], v[188:191], v[220:223], v[66:69]
	s_setprio 0
	s_barrier
; #define PG8_BAR __builtin_amdgcn_s_barrier()
;     __device__ __forceinline__ void operator()(const f32x4 (&acc)[2][2][4][2], const Unit& u, int wr, int wc, int fr, int fq, const float (&rsv)[8]) const {
;     ...
;             for (int m = 0; m < 4; ++m) { bf16_t* rowp = O + (size_t)(row0 + ai * HALF + m * 16) * ldc + col0; float r[8]; const float rr = rsv[ai * 4 + m];
; #pragma unroll
;                 for (int n = 0; n < 2; ++n)
; #pragma unroll
; template <class Epi, class Sched, bool ALIGN_EPI = false, bool SP2 = false>
; __device__ __forceinline__ void gemm_phase(PG8_LAS unsigned char* lds, const Gemm g, const Sched& S, const Epi& E, const int tid_in) {
;     ...
;             PG8_LDA(At, 1, 1); PG8_STAGE(PG8_SB(1, 0), b3, voffB); PG8_STAGE(PG8_SB(1, 1), b3 + hstep, voffB); PG8_STAGE(PG8_SA(1, 0), a3, voffA);
;             PG8_WAIT_V(8); PG8_WAIT_L(0); PG8_BAR; PG8_MMA(1, 0, At, B0); PG8_MMA(1, 1, At, B1); PG8_BAR; PG8_SCHED;
;             } else {
;             PG8_LDB(B0, 0, 0); PG8_SCHED; PG8_LDA(At, 0, 0); PG8_STAGE(PG8_SA(1, 1), a1 + hstep, voffA);
;             PG8_WAIT_L(8); PG8_BAR; PG8_WAIT_L(0); PG8_MMA(0, 0, At, B0); PG8_BAR; PG8_SCHED;
;             PG8_LDB(B1, 0, 1); PG8_STAGE(PG8_SB(0, 0), b2, voffB);
;             PG8_BAR; PG8_WAIT_L(0); PG8_MMA(0, 1, At, B1); PG8_BAR;
;             PG8_LDA(At, 0, 1); PG8_STAGE(PG8_SA(0, 0), a2, voffA);
;             PG8_BAR; PG8_WAIT_L(0); PG8_MMA(1, 0, At, B0); PG8_BAR; PG8_SCHED;
;             PG8_STAGE(PG8_SB(0, 1), b2 + hstep, voffB);
;             PG8_WAIT_V(6); PG8_BAR; PG8_MMA(1, 1, At, B1); PG8_BAR;
;             PG8_LDB(B0, 1, 0); PG8_SCHED; PG8_LDA(At, 1, 0); PG8_STAGE(PG8_SA(0, 1), a2 + hstep, voffA);
;             PG8_WAIT_L(8); PG8_BAR; PG8_WAIT_L(0); PG8_MMA(0, 0, At, B0); PG8_BAR; PG8_SCHED;
;             PG8_LDB(B1, 1, 1); PG8_STAGE(PG8_SB(1, 0), b3, voffB);
;             PG8_BAR; PG8_WAIT_L(0); PG8_MMA(0, 1, At, B1); PG8_BAR;
;             PG8_LDA(At, 1, 1); PG8_STAGE(PG8_SA(1, 0), a3, voffA);
;             PG8_BAR; PG8_WAIT_L(0); PG8_MMA(1, 0, At, B0); PG8_BAR; PG8_SCHED;
;             PG8_STAGE(PG8_SB(1, 1), b3 + hstep, voffB);
;             PG8_WAIT_V(6); PG8_BAR; PG8_MMA(1, 1, At, B1); PG8_BAR;
;             }
;         }
;         if constexpr (ALIGN_EPI) { if (wr == 0) PG8_BAR; }
;         if constexpr (!Epi::AFTER_DRAIN) { E(acc, cur, wr, wc, fr, fq, rsv); S.done(cur); }
	s_add_i32 s62, s64, s21
	s_mov_b32 m0, s62
	ds_read_b128 v[192:195], v149 offset:49152
	ds_read_b128 v[196:199], v149 offset:50176
	ds_read_b128 v[200:203], v149 offset:51200
	ds_read_b128 v[204:207], v149 offset:52224
	ds_read_b128 v[208:211], v149 offset:53248
	ds_read_b128 v[212:215], v149 offset:54272
	ds_read_b128 v[216:219], v149 offset:55296
	ds_read_b128 v[220:223], v149 offset:56320
	s_add_u32 s44, s72, 0x80
	s_addc_u32 s45, s73, 0
	global_load_lds_dwordx4 v0, s[44:45]
	s_add_i32 m0, s62, 0x2000
	s_add_u32 s62, s72, 0x40080
	s_addc_u32 s63, s73, 0
	s_add_i32 s64, s76, s21
	global_load_lds_dwordx4 v130, s[44:45]
	s_mov_b32 m0, s64
	s_nop 0
	global_load_lds_dwordx4 v0, s[62:63]
	s_add_i32 m0, s64, 0x2000
	s_nop 0
	global_load_lds_dwordx4 v130, s[62:63]
	s_mov_b32 m0, s36
	s_nop 0
	s_add_u32 s44, s74, 0x80
	s_addc_u32 s45, s75, 0
	global_load_lds_dwordx4 v134, s[44:45]
	s_mov_b32 m0, s37
	s_nop 0
	global_load_lds_dwordx4 v132, s[44:45]
	s_waitcnt vmcnt(8)
	s_waitcnt lgkmcnt(0)
	s_barrier
	s_setprio 1
	s_waitcnt lgkmcnt(0)
	v_mfma_f32_16x16x32_bf16 v[62:65], v[160:163], v[192:195], v[62:65]
	v_mfma_f32_16x16x32_bf16 v[54:57], v[168:171], v[192:195], v[54:57]
	v_mfma_f32_16x16x32_bf16 v[46:49], v[160:163], v[200:203], v[46:49]
	v_mfma_f32_16x16x32_bf16 v[38:41], v[168:171], v[200:203], v[38:41]
	v_mfma_f32_16x16x32_bf16 v[30:33], v[160:163], v[208:211], v[30:33]
	v_mfma_f32_16x16x32_bf16 v[22:25], v[168:171], v[208:211], v[22:25]
	v_mfma_f32_16x16x32_bf16 v[14:17], v[160:163], v[216:219], v[14:17]
	v_mfma_f32_16x16x32_bf16 v[6:9], v[168:171], v[216:219], v[6:9]
	v_mfma_f32_16x16x32_bf16 v[62:65], v[164:167], v[196:199], v[62:65]
	v_mfma_f32_16x16x32_bf16 v[54:57], v[172:175], v[196:199], v[54:57]
	v_mfma_f32_16x16x32_bf16 v[46:49], v[164:167], v[204:207], v[46:49]
	v_mfma_f32_16x16x32_bf16 v[38:41], v[172:175], v[204:207], v[38:41]
	v_mfma_f32_16x16x32_bf16 v[30:33], v[164:167], v[212:215], v[30:33]
	v_mfma_f32_16x16x32_bf16 v[22:25], v[172:175], v[212:215], v[22:25]
	v_mfma_f32_16x16x32_bf16 v[14:17], v[164:167], v[220:223], v[14:17]
	v_mfma_f32_16x16x32_bf16 v[6:9], v[172:175], v[220:223], v[6:9]
	s_setprio 0
	s_setprio 1
	v_mfma_f32_16x16x32_bf16 v[58:61], v[176:179], v[192:195], v[58:61]
	v_mfma_f32_16x16x32_bf16 v[50:53], v[184:187], v[192:195], v[50:53]
	v_mfma_f32_16x16x32_bf16 v[42:45], v[176:179], v[200:203], v[42:45]
	v_mfma_f32_16x16x32_bf16 v[34:37], v[184:187], v[200:203], v[34:37]
	v_mfma_f32_16x16x32_bf16 v[26:29], v[176:179], v[208:211], v[26:29]
	v_mfma_f32_16x16x32_bf16 v[18:21], v[184:187], v[208:211], v[18:21]
	v_mfma_f32_16x16x32_bf16 v[10:13], v[176:179], v[216:219], v[10:13]
	v_mfma_f32_16x16x32_bf16 v[2:5], v[184:187], v[216:219], v[2:5]
	v_mfma_f32_16x16x32_bf16 v[58:61], v[180:183], v[196:199], v[58:61]
	v_mfma_f32_16x16x32_bf16 v[50:53], v[188:191], v[196:199], v[50:53]
	v_mfma_f32_16x16x32_bf16 v[42:45], v[180:183], v[204:207], v[42:45]
	v_mfma_f32_16x16x32_bf16 v[34:37], v[188:191], v[204:207], v[34:37]
	v_mfma_f32_16x16x32_bf16 v[26:29], v[180:183], v[212:215], v[26:29]
	v_mfma_f32_16x16x32_bf16 v[18:21], v[188:191], v[212:215], v[18:21]
	v_mfma_f32_16x16x32_bf16 v[10:13], v[180:183], v[220:223], v[10:13]
	v_mfma_f32_16x16x32_bf16 v[2:5], v[188:191], v[220:223], v[2:5]
	s_setprio 0
	s_barrier
	s_add_i32 s61, s61, 2
	s_add_u32 s70, s70, 0x100
	s_addc_u32 s71, s71, 0
	s_add_u32 s59, s59, 0x100
	s_addc_u32 s60, s60, 0
	s_cmp_gt_u32 s61, 13
	s_cbranch_scc0 .LBB0_622
	s_mov_b64 s[44:45], 0x80
	s_and_b64 vcc, exec, s[16:17]
	s_cbranch_vccz .LBB0_625
	s_barrier
.LBB0_625:
	v_mov_b32_e32 v164, v126
	v_mov_b32_e32 v165, v122
	s_waitcnt vmcnt(8)
	v_pk_mul_f32 v[164:165], v[158:159], v[164:165] op_sel_hi:[0,1]
	v_mul_f32_e32 v122, 0xbfb8aa3b, v164
	v_exp_f32_e32 v122, v122
	v_lshl_or_b32 v160, s42, 7, v147
	v_ashrrev_i32_e32 v161, 31, v160
	v_mov_b64_e32 v[154:155], s[12:13]
	v_add_f32_e32 v122, 1.0, v122
	v_rcp_f32_e32 v122, v122
	v_mad_i64_i32 v[162:163], s[42:43], v142, s65, v[154:155]
	v_add_u32_e32 v143, 0x80, v142
	v_mul_f32_e32 v122, v164, v122
	v_mul_f32_e32 v126, v122, v165
	v_mov_b32_e32 v122, v127
	v_pk_mul_f32 v[122:123], v[158:159], v[122:123] op_sel_hi:[0,1]
	v_mul_f32_e32 v127, 0xbfb8aa3b, v122
	v_exp_f32_e32 v127, v127
	s_mov_b64 s[70:71], -1
	s_andn2_b64 vcc, exec, s[4:5]
	v_add_f32_e32 v127, 1.0, v127
	v_rcp_f32_e32 v127, v127
	s_nop 0
	v_mul_f32_e32 v122, v122, v127
	v_mul_f32_e32 v127, v122, v123
	v_mov_b32_e32 v122, v128
	v_mov_b32_e32 v123, v124
	v_pk_mul_f32 v[122:123], v[158:159], v[122:123] op_sel_hi:[0,1]
	v_mul_f32_e32 v124, 0xbfb8aa3b, v122
	v_exp_f32_e32 v124, v124
	s_nop 0
	v_add_f32_e32 v124, 1.0, v124
	v_rcp_f32_e32 v124, v124
	s_nop 0
	v_mul_f32_e32 v122, v122, v124
	v_mov_b32_e32 v124, v129
	v_mul_f32_e32 v128, v122, v123
	v_pk_mul_f32 v[122:123], v[158:159], v[124:125] op_sel_hi:[0,1]
	v_mul_f32_e32 v124, 0xbfb8aa3b, v122
	v_exp_f32_e32 v124, v124
	s_nop 0
	v_add_f32_e32 v124, 1.0, v124
	v_rcp_f32_e32 v124, v124
	s_nop 0
	v_mul_f32_e32 v122, v122, v124
	v_mul_f32_e32 v124, v122, v123
	v_mov_b32_e32 v122, v118
	v_mov_b32_e32 v123, v114
	v_pk_mul_f32 v[122:123], v[158:159], v[122:123] op_sel_hi:[0,1]
	v_mul_f32_e32 v114, 0xbfb8aa3b, v122
	v_exp_f32_e32 v114, v114
	s_nop 0
	v_add_f32_e32 v114, 1.0, v114
	v_rcp_f32_e32 v114, v114
	s_nop 0
	v_mul_f32_e32 v114, v122, v114
	v_mul_f32_e32 v118, v114, v123
	v_mov_b32_e32 v114, v119
	v_pk_mul_f32 v[114:115], v[158:159], v[114:115] op_sel_hi:[0,1]
	v_mul_f32_e32 v119, 0xbfb8aa3b, v114
	v_exp_f32_e32 v119, v119
	s_nop 0
	v_add_f32_e32 v119, 1.0, v119
	v_rcp_f32_e32 v119, v119
	s_nop 0
	v_mul_f32_e32 v114, v114, v119
	v_mul_f32_e32 v119, v114, v115
; __device__ __forceinline__ unsigned cvt_pk_bf16(float lo, float hi) { unsigned r; asm volatile("v_cvt_pk_bf16_f32 %0, %1, %2" : "=v"(r) : "v"(lo), "v"(hi)); return r; }
;     __device__ __forceinline__ void operator()(const f32x4 (&acc)[2][2][4][2], const Unit& u, int wr, int wc, int fr, int fq, const float (&rsv)[8]) const {
;     ...
;             for (int m = 0; m < 4; ++m) { bf16_t* rowp = O + (size_t)(row0 + ai * HALF + m * 16) * ldc + col0; float r[8]; const float rr = rsv[ai * 4 + m];
; #pragma unroll
;                 for (int n = 0; n < 2; ++n)
; #pragma unroll
;                     for (int j = 0; j < 4; ++j) { const float g = acc[ai][0][m][n][j] * rr, up = acc[ai][1][m][n][j] * rr;
;                         const float e = __builtin_amdgcn_exp2f(g * -1.4426950408889634f); r[n * 4 + j] = g * __builtin_amdgcn_rcpf(1.0f + e) * up; }
;                 u32x4 w; w.x = cvt_pk_bf16(r[0], r[1]); w.y = cvt_pk_bf16(r[2], r[3]); w.z = cvt_pk_bf16(r[4], r[5]); w.w = cvt_pk_bf16(r[6], r[7]);
;                 *(u32x4*)rowp = w; }
	v_mov_b32_e32 v114, v120
	v_mov_b32_e32 v115, v116
	v_pk_mul_f32 v[114:115], v[158:159], v[114:115] op_sel_hi:[0,1]
	v_mul_f32_e32 v116, 0xbfb8aa3b, v114
	v_exp_f32_e32 v116, v116
	s_nop 0
	v_add_f32_e32 v116, 1.0, v116
	v_rcp_f32_e32 v116, v116
	s_nop 0
	v_mul_f32_e32 v114, v114, v116
	v_mov_b32_e32 v116, v121
	v_mul_f32_e32 v122, v114, v115
	v_pk_mul_f32 v[114:115], v[158:159], v[116:117] op_sel_hi:[0,1]
	v_mul_f32_e32 v116, 0xbfb8aa3b, v114
	v_exp_f32_e32 v116, v116
	s_nop 0
	v_add_f32_e32 v116, 1.0, v116
	v_rcp_f32_e32 v116, v116
	s_nop 0
	v_mul_f32_e32 v114, v114, v116
	v_mul_f32_e32 v123, v114, v115
	v_lshlrev_b64 v[114:115], 1, v[160:161]
	v_lshl_add_u64 v[120:121], v[162:163], 0, v[114:115]
	v_cvt_pk_bf16_f32 v116, v126, v127
	v_cvt_pk_bf16_f32 v117, v128, v124
	v_cvt_pk_bf16_f32 v118, v118, v119
	v_cvt_pk_bf16_f32 v119, v122, v123
	global_store_dwordx4 v[120:121], v[116:119], off
	s_nop 1
	v_mov_b32_e32 v118, v110
	v_mov_b32_e32 v119, v106
	v_pk_mul_f32 v[118:119], v[156:157], v[118:119] op_sel_hi:[0,1]
	v_mul_f32_e32 v106, 0xbfb8aa3b, v118
	v_exp_f32_e32 v106, v106
	v_or_b32_e32 v116, 16, v142
	v_mad_i64_i32 v[116:117], s[42:43], v116, s65, v[154:155]
	v_add_f32_e32 v106, 1.0, v106
	v_rcp_f32_e32 v106, v106
	s_nop 0
	v_mul_f32_e32 v106, v118, v106
	v_mul_f32_e32 v110, v106, v119
	v_mov_b32_e32 v106, v111
	v_pk_mul_f32 v[106:107], v[156:157], v[106:107] op_sel_hi:[0,1]
	v_mul_f32_e32 v111, 0xbfb8aa3b, v106
	v_exp_f32_e32 v111, v111
	s_nop 0
	v_add_f32_e32 v111, 1.0, v111
	v_rcp_f32_e32 v111, v111
	s_nop 0
	v_mul_f32_e32 v106, v106, v111
	v_mul_f32_e32 v111, v106, v107
	v_mov_b32_e32 v106, v112
	v_mov_b32_e32 v107, v108
	v_pk_mul_f32 v[106:107], v[156:157], v[106:107] op_sel_hi:[0,1]
	v_mul_f32_e32 v108, 0xbfb8aa3b, v106
	v_exp_f32_e32 v108, v108
	s_nop 0
	v_add_f32_e32 v108, 1.0, v108
	v_rcp_f32_e32 v108, v108
	s_nop 0
	v_mul_f32_e32 v106, v106, v108
	v_mov_b32_e32 v108, v113
	v_mul_f32_e32 v112, v106, v107
	v_pk_mul_f32 v[106:107], v[156:157], v[108:109] op_sel_hi:[0,1]
	v_mul_f32_e32 v108, 0xbfb8aa3b, v106
	v_exp_f32_e32 v108, v108
	s_nop 0
	v_add_f32_e32 v108, 1.0, v108
	v_rcp_f32_e32 v108, v108
	s_nop 0
	v_mul_f32_e32 v106, v106, v108
	v_mul_f32_e32 v108, v106, v107
	v_mov_b32_e32 v106, v102
	v_mov_b32_e32 v107, v98
	v_pk_mul_f32 v[106:107], v[156:157], v[106:107] op_sel_hi:[0,1]
	v_mul_f32_e32 v98, 0xbfb8aa3b, v106
	v_exp_f32_e32 v98, v98
	s_nop 0
	v_add_f32_e32 v98, 1.0, v98
	v_rcp_f32_e32 v98, v98
	s_nop 0
	v_mul_f32_e32 v98, v106, v98
	v_mul_f32_e32 v106, v98, v107
	v_mov_b32_e32 v98, v103
	v_pk_mul_f32 v[98:99], v[156:157], v[98:99] op_sel_hi:[0,1]
	v_mul_f32_e32 v102, 0xbfb8aa3b, v98
	v_exp_f32_e32 v102, v102
	s_nop 0
	v_add_f32_e32 v102, 1.0, v102
	v_rcp_f32_e32 v102, v102
	s_nop 0
	v_mul_f32_e32 v98, v98, v102
	v_mul_f32_e32 v107, v98, v99
	v_mov_b32_e32 v98, v104
	v_mov_b32_e32 v99, v100
	v_pk_mul_f32 v[98:99], v[156:157], v[98:99] op_sel_hi:[0,1]
	v_mul_f32_e32 v100, 0xbfb8aa3b, v98
	v_exp_f32_e32 v100, v100
	v_lshl_add_u64 v[102:103], v[116:117], 0, v[114:115]
	v_add_f32_e32 v100, 1.0, v100
	v_rcp_f32_e32 v100, v100
	s_nop 0
	v_mul_f32_e32 v98, v98, v100
	v_mov_b32_e32 v100, v105
	v_mul_f32_e32 v104, v98, v99
	v_pk_mul_f32 v[98:99], v[156:157], v[100:101] op_sel_hi:[0,1]
	v_mul_f32_e32 v100, 0xbfb8aa3b, v98
	v_exp_f32_e32 v100, v100
	s_nop 0
	v_add_f32_e32 v100, 1.0, v100
	v_rcp_f32_e32 v100, v100
	s_nop 0
	v_mul_f32_e32 v98, v98, v100
	v_mul_f32_e32 v101, v98, v99
	v_cvt_pk_bf16_f32 v98, v110, v111
	v_cvt_pk_bf16_f32 v99, v112, v108
	v_cvt_pk_bf16_f32 v100, v106, v107
	v_cvt_pk_bf16_f32 v101, v104, v101
	global_store_dwordx4 v[102:103], v[98:101], off
	s_nop 1
	v_mov_b32_e32 v100, v94
	v_mov_b32_e32 v101, v90
	v_pk_mul_f32 v[100:101], v[152:153], v[100:101] op_sel_hi:[0,1]
	v_mul_f32_e32 v90, 0xbfb8aa3b, v100
	v_exp_f32_e32 v90, v90
	v_or_b32_e32 v98, 32, v142
	v_mad_i64_i32 v[98:99], s[42:43], v98, s65, v[154:155]
	v_add_f32_e32 v90, 1.0, v90
	v_rcp_f32_e32 v90, v90
	s_nop 0
	v_mul_f32_e32 v90, v100, v90
	v_mul_f32_e32 v94, v90, v101
	v_mov_b32_e32 v90, v95
	v_pk_mul_f32 v[90:91], v[152:153], v[90:91] op_sel_hi:[0,1]
	v_mul_f32_e32 v95, 0xbfb8aa3b, v90
	v_exp_f32_e32 v95, v95
	s_nop 0
	v_add_f32_e32 v95, 1.0, v95
	v_rcp_f32_e32 v95, v95
	s_nop 0
	v_mul_f32_e32 v90, v90, v95
	v_mul_f32_e32 v95, v90, v91
	v_mov_b32_e32 v90, v96
	v_mov_b32_e32 v91, v92
	v_pk_mul_f32 v[90:91], v[152:153], v[90:91] op_sel_hi:[0,1]
	v_mul_f32_e32 v92, 0xbfb8aa3b, v90
	v_exp_f32_e32 v92, v92
	s_nop 0
	v_add_f32_e32 v92, 1.0, v92
	v_rcp_f32_e32 v92, v92
	s_nop 0
	v_mul_f32_e32 v90, v90, v92
	v_mov_b32_e32 v92, v97
	v_mul_f32_e32 v96, v90, v91
	v_pk_mul_f32 v[90:91], v[152:153], v[92:93] op_sel_hi:[0,1]
	v_mul_f32_e32 v92, 0xbfb8aa3b, v90
	v_exp_f32_e32 v92, v92
	s_nop 0
	v_add_f32_e32 v92, 1.0, v92
	v_rcp_f32_e32 v92, v92
	s_nop 0
	v_mul_f32_e32 v90, v90, v92
	v_mul_f32_e32 v92, v90, v91
	v_mov_b32_e32 v90, v86
	v_mov_b32_e32 v91, v82
	v_pk_mul_f32 v[90:91], v[152:153], v[90:91] op_sel_hi:[0,1]
	v_mul_f32_e32 v82, 0xbfb8aa3b, v90
	v_exp_f32_e32 v82, v82
	s_nop 0
	v_add_f32_e32 v82, 1.0, v82
	v_rcp_f32_e32 v82, v82
	s_nop 0
	v_mul_f32_e32 v82, v90, v82
	v_mul_f32_e32 v90, v82, v91
	v_mov_b32_e32 v82, v87
	v_pk_mul_f32 v[82:83], v[152:153], v[82:83] op_sel_hi:[0,1]
	v_mul_f32_e32 v86, 0xbfb8aa3b, v82
	v_exp_f32_e32 v86, v86
	s_nop 0
	v_add_f32_e32 v86, 1.0, v86
	v_rcp_f32_e32 v86, v86
	s_nop 0
	v_mul_f32_e32 v82, v82, v86
	v_mul_f32_e32 v91, v82, v83
	v_mov_b32_e32 v82, v88
	v_mov_b32_e32 v83, v84
	v_pk_mul_f32 v[82:83], v[152:153], v[82:83] op_sel_hi:[0,1]
	v_mul_f32_e32 v84, 0xbfb8aa3b, v82
	v_exp_f32_e32 v84, v84
; __device__ __forceinline__ unsigned cvt_pk_bf16(float lo, float hi) { unsigned r; asm volatile("v_cvt_pk_bf16_f32 %0, %1, %2" : "=v"(r) : "v"(lo), "v"(hi)); return r; }
;     __device__ __forceinline__ void operator()(const f32x4 (&acc)[2][2][4][2], const Unit& u, int wr, int wc, int fr, int fq, const float (&rsv)[8]) const {
;     ...
;             for (int m = 0; m < 4; ++m) { bf16_t* rowp = O + (size_t)(row0 + ai * HALF + m * 16) * ldc + col0; float r[8]; const float rr = rsv[ai * 4 + m];
; #pragma unroll
;                 for (int n = 0; n < 2; ++n)
; #pragma unroll
;                     for (int j = 0; j < 4; ++j) { const float g = acc[ai][0][m][n][j] * rr, up = acc[ai][1][m][n][j] * rr;
;                         const float e = __builtin_amdgcn_exp2f(g * -1.4426950408889634f); r[n * 4 + j] = g * __builtin_amdgcn_rcpf(1.0f + e) * up; }
;                 u32x4 w; w.x = cvt_pk_bf16(r[0], r[1]); w.y = cvt_pk_bf16(r[2], r[3]); w.z = cvt_pk_bf16(r[4], r[5]); w.w = cvt_pk_bf16(r[6], r[7]);
;                 *(u32x4*)rowp = w; }
	v_lshl_add_u64 v[86:87], v[98:99], 0, v[114:115]
	v_add_f32_e32 v84, 1.0, v84
	v_rcp_f32_e32 v84, v84
	s_nop 0
	v_mul_f32_e32 v82, v82, v84
	v_mov_b32_e32 v84, v89
	v_mul_f32_e32 v88, v82, v83
	v_pk_mul_f32 v[82:83], v[152:153], v[84:85] op_sel_hi:[0,1]
	v_mul_f32_e32 v84, 0xbfb8aa3b, v82
	v_exp_f32_e32 v84, v84
	s_nop 0
	v_add_f32_e32 v84, 1.0, v84
	v_rcp_f32_e32 v84, v84
	s_nop 0
	v_mul_f32_e32 v82, v82, v84
	v_mul_f32_e32 v85, v82, v83
	v_cvt_pk_bf16_f32 v82, v94, v95
	v_cvt_pk_bf16_f32 v83, v96, v92
	v_cvt_pk_bf16_f32 v84, v90, v91
	v_cvt_pk_bf16_f32 v85, v88, v85
	global_store_dwordx4 v[86:87], v[82:85], off
	s_nop 1
	v_mov_b32_e32 v84, v78
	v_mov_b32_e32 v85, v74
	v_pk_mul_f32 v[84:85], v[150:151], v[84:85] op_sel_hi:[0,1]
	v_mul_f32_e32 v74, 0xbfb8aa3b, v84
	v_exp_f32_e32 v74, v74
	v_or_b32_e32 v82, 48, v142
	v_mad_i64_i32 v[82:83], s[42:43], v82, s65, v[154:155]
	v_add_f32_e32 v74, 1.0, v74
	v_rcp_f32_e32 v74, v74
	s_nop 0
	v_mul_f32_e32 v74, v84, v74
	v_mul_f32_e32 v78, v74, v85
	v_mov_b32_e32 v74, v79
	v_pk_mul_f32 v[74:75], v[150:151], v[74:75] op_sel_hi:[0,1]
	v_mul_f32_e32 v79, 0xbfb8aa3b, v74
	v_exp_f32_e32 v79, v79
	s_nop 0
	v_add_f32_e32 v79, 1.0, v79
	v_rcp_f32_e32 v79, v79
	s_nop 0
	v_mul_f32_e32 v74, v74, v79
	v_mul_f32_e32 v79, v74, v75
	v_mov_b32_e32 v74, v80
	v_mov_b32_e32 v75, v76
	v_pk_mul_f32 v[74:75], v[150:151], v[74:75] op_sel_hi:[0,1]
	v_mul_f32_e32 v76, 0xbfb8aa3b, v74
	v_exp_f32_e32 v76, v76
	s_nop 0
	v_add_f32_e32 v76, 1.0, v76
	v_rcp_f32_e32 v76, v76
	s_nop 0
	v_mul_f32_e32 v74, v74, v76
	v_mov_b32_e32 v76, v81
	v_mul_f32_e32 v80, v74, v75
	v_pk_mul_f32 v[74:75], v[150:151], v[76:77] op_sel_hi:[0,1]
	v_mul_f32_e32 v76, 0xbfb8aa3b, v74
	v_exp_f32_e32 v76, v76
	s_nop 0
	v_add_f32_e32 v76, 1.0, v76
	v_rcp_f32_e32 v76, v76
	s_nop 0
	v_mul_f32_e32 v74, v74, v76
	v_mul_f32_e32 v76, v74, v75
	v_mov_b32_e32 v74, v70
	v_mov_b32_e32 v75, v66
	v_pk_mul_f32 v[74:75], v[150:151], v[74:75] op_sel_hi:[0,1]
	v_mul_f32_e32 v66, 0xbfb8aa3b, v74
	v_exp_f32_e32 v66, v66
	s_nop 0
	v_add_f32_e32 v66, 1.0, v66
	v_rcp_f32_e32 v66, v66
	s_nop 0
	v_mul_f32_e32 v66, v74, v66
	v_mul_f32_e32 v74, v66, v75
	v_mov_b32_e32 v66, v71
	v_pk_mul_f32 v[66:67], v[150:151], v[66:67] op_sel_hi:[0,1]
	v_mul_f32_e32 v70, 0xbfb8aa3b, v66
	v_exp_f32_e32 v70, v70
	s_nop 0
	v_add_f32_e32 v70, 1.0, v70
	v_rcp_f32_e32 v70, v70
	s_nop 0
	v_mul_f32_e32 v66, v66, v70
	v_mul_f32_e32 v75, v66, v67
	v_mov_b32_e32 v66, v72
	v_mov_b32_e32 v67, v68
	v_pk_mul_f32 v[66:67], v[150:151], v[66:67] op_sel_hi:[0,1]
	v_mul_f32_e32 v68, 0xbfb8aa3b, v66
	v_exp_f32_e32 v68, v68
	v_lshl_add_u64 v[70:71], v[82:83], 0, v[114:115]
	v_add_f32_e32 v68, 1.0, v68
	v_rcp_f32_e32 v68, v68
	s_nop 0
	v_mul_f32_e32 v66, v66, v68
	v_mov_b32_e32 v68, v73
	v_mul_f32_e32 v72, v66, v67
	v_pk_mul_f32 v[66:67], v[150:151], v[68:69] op_sel_hi:[0,1]
	v_mul_f32_e32 v68, 0xbfb8aa3b, v66
	v_exp_f32_e32 v68, v68
	s_nop 0
	v_add_f32_e32 v68, 1.0, v68
	v_rcp_f32_e32 v68, v68
	s_nop 0
	v_mul_f32_e32 v66, v66, v68
	v_mul_f32_e32 v69, v66, v67
	v_cvt_pk_bf16_f32 v66, v78, v79
	v_cvt_pk_bf16_f32 v67, v80, v76
	v_cvt_pk_bf16_f32 v68, v74, v75
	v_cvt_pk_bf16_f32 v69, v72, v69
	global_store_dwordx4 v[70:71], v[66:69], off
	s_nop 1
	v_mov_b32_e32 v68, v62
	v_mov_b32_e32 v69, v58
	v_pk_mul_f32 v[68:69], v[148:149], v[68:69] op_sel_hi:[0,1]
	v_mul_f32_e32 v58, 0xbfb8aa3b, v68
	v_exp_f32_e32 v58, v58
	v_mad_i64_i32 v[66:67], s[42:43], v143, s65, v[154:155]
	v_add_f32_e32 v58, 1.0, v58
	v_rcp_f32_e32 v58, v58
	s_nop 0
	v_mul_f32_e32 v58, v68, v58
	v_mul_f32_e32 v62, v58, v69
	v_mov_b32_e32 v58, v63
	v_pk_mul_f32 v[58:59], v[148:149], v[58:59] op_sel_hi:[0,1]
	v_mul_f32_e32 v63, 0xbfb8aa3b, v58
	v_exp_f32_e32 v63, v63
	s_nop 0
	v_add_f32_e32 v63, 1.0, v63
	v_rcp_f32_e32 v63, v63
	s_nop 0
	v_mul_f32_e32 v58, v58, v63
	v_mul_f32_e32 v63, v58, v59
	v_mov_b32_e32 v58, v64
	v_mov_b32_e32 v59, v60
	v_pk_mul_f32 v[58:59], v[148:149], v[58:59] op_sel_hi:[0,1]
	v_mul_f32_e32 v60, 0xbfb8aa3b, v58
	v_exp_f32_e32 v60, v60
	s_nop 0
	v_add_f32_e32 v60, 1.0, v60
	v_rcp_f32_e32 v60, v60
	s_nop 0
	v_mul_f32_e32 v58, v58, v60
	v_mov_b32_e32 v60, v65
	v_mul_f32_e32 v64, v58, v59
	v_pk_mul_f32 v[58:59], v[148:149], v[60:61] op_sel_hi:[0,1]
	v_mul_f32_e32 v60, 0xbfb8aa3b, v58
	v_exp_f32_e32 v60, v60
	s_nop 0
	v_add_f32_e32 v60, 1.0, v60
	v_rcp_f32_e32 v60, v60
	s_nop 0
	v_mul_f32_e32 v58, v58, v60
	v_mul_f32_e32 v60, v58, v59
	v_mov_b32_e32 v58, v54
	v_mov_b32_e32 v59, v50
	v_pk_mul_f32 v[58:59], v[148:149], v[58:59] op_sel_hi:[0,1]
	v_mul_f32_e32 v50, 0xbfb8aa3b, v58
	v_exp_f32_e32 v50, v50
	s_nop 0
	v_add_f32_e32 v50, 1.0, v50
	v_rcp_f32_e32 v50, v50
	s_nop 0
	v_mul_f32_e32 v50, v58, v50
	v_mul_f32_e32 v58, v50, v59
	v_mov_b32_e32 v50, v55
	v_pk_mul_f32 v[50:51], v[148:149], v[50:51] op_sel_hi:[0,1]
	v_mul_f32_e32 v54, 0xbfb8aa3b, v50
	v_exp_f32_e32 v54, v54
	s_nop 0
	v_add_f32_e32 v54, 1.0, v54
	v_rcp_f32_e32 v54, v54
	s_nop 0
	v_mul_f32_e32 v50, v50, v54
	v_mul_f32_e32 v59, v50, v51
	v_mov_b32_e32 v50, v56
	v_mov_b32_e32 v51, v52
	v_pk_mul_f32 v[50:51], v[148:149], v[50:51] op_sel_hi:[0,1]
	v_mul_f32_e32 v52, 0xbfb8aa3b, v50
	v_exp_f32_e32 v52, v52
	v_lshl_add_u64 v[54:55], v[66:67], 0, v[114:115]
	v_add_f32_e32 v52, 1.0, v52
	v_rcp_f32_e32 v52, v52
	s_nop 0
	v_mul_f32_e32 v50, v50, v52
	v_mov_b32_e32 v52, v57
	v_mul_f32_e32 v56, v50, v51
	v_pk_mul_f32 v[50:51], v[148:149], v[52:53] op_sel_hi:[0,1]
	v_mul_f32_e32 v52, 0xbfb8aa3b, v50
	v_exp_f32_e32 v52, v52
	s_nop 0
	v_add_f32_e32 v52, 1.0, v52
	v_rcp_f32_e32 v52, v52
	s_nop 0
	v_mul_f32_e32 v50, v50, v52
	v_mul_f32_e32 v53, v50, v51
	v_cvt_pk_bf16_f32 v50, v62, v63
; __device__ __forceinline__ unsigned cvt_pk_bf16(float lo, float hi) { unsigned r; asm volatile("v_cvt_pk_bf16_f32 %0, %1, %2" : "=v"(r) : "v"(lo), "v"(hi)); return r; }
;     __device__ __forceinline__ void operator()(const f32x4 (&acc)[2][2][4][2], const Unit& u, int wr, int wc, int fr, int fq, const float (&rsv)[8]) const {
;     ...
;             for (int m = 0; m < 4; ++m) { bf16_t* rowp = O + (size_t)(row0 + ai * HALF + m * 16) * ldc + col0; float r[8]; const float rr = rsv[ai * 4 + m];
; #pragma unroll
;                 for (int n = 0; n < 2; ++n)
; #pragma unroll
;                     for (int j = 0; j < 4; ++j) { const float g = acc[ai][0][m][n][j] * rr, up = acc[ai][1][m][n][j] * rr;
;                         const float e = __builtin_amdgcn_exp2f(g * -1.4426950408889634f); r[n * 4 + j] = g * __builtin_amdgcn_rcpf(1.0f + e) * up; }
;                 u32x4 w; w.x = cvt_pk_bf16(r[0], r[1]); w.y = cvt_pk_bf16(r[2], r[3]); w.z = cvt_pk_bf16(r[4], r[5]); w.w = cvt_pk_bf16(r[6], r[7]);
;                 *(u32x4*)rowp = w; }
	v_cvt_pk_bf16_f32 v51, v64, v60
	v_cvt_pk_bf16_f32 v52, v58, v59
	v_cvt_pk_bf16_f32 v53, v56, v53
	global_store_dwordx4 v[54:55], v[50:53], off
	s_nop 1
	v_mov_b32_e32 v52, v46
	v_mov_b32_e32 v53, v42
	v_pk_mul_f32 v[52:53], v[146:147], v[52:53] op_sel_hi:[0,1]
	v_mul_f32_e32 v42, 0xbfb8aa3b, v52
	v_exp_f32_e32 v42, v42
	v_add_u32_e32 v50, 0x90, v142
	v_mad_i64_i32 v[50:51], s[42:43], v50, s65, v[154:155]
	v_add_f32_e32 v42, 1.0, v42
	v_rcp_f32_e32 v42, v42
	s_nop 0
	v_mul_f32_e32 v42, v52, v42
	v_mul_f32_e32 v46, v42, v53
	v_mov_b32_e32 v42, v47
	v_pk_mul_f32 v[42:43], v[146:147], v[42:43] op_sel_hi:[0,1]
	v_mul_f32_e32 v47, 0xbfb8aa3b, v42
	v_exp_f32_e32 v47, v47
	s_nop 0
	v_add_f32_e32 v47, 1.0, v47
	v_rcp_f32_e32 v47, v47
	s_nop 0
	v_mul_f32_e32 v42, v42, v47
	v_mul_f32_e32 v47, v42, v43
	v_mov_b32_e32 v42, v48
	v_mov_b32_e32 v43, v44
	v_pk_mul_f32 v[42:43], v[146:147], v[42:43] op_sel_hi:[0,1]
	v_mul_f32_e32 v44, 0xbfb8aa3b, v42
	v_exp_f32_e32 v44, v44
	s_nop 0
	v_add_f32_e32 v44, 1.0, v44
	v_rcp_f32_e32 v44, v44
	s_nop 0
	v_mul_f32_e32 v42, v42, v44
	v_mov_b32_e32 v44, v49
	v_mul_f32_e32 v48, v42, v43
	v_pk_mul_f32 v[42:43], v[146:147], v[44:45] op_sel_hi:[0,1]
	v_mul_f32_e32 v44, 0xbfb8aa3b, v42
	v_exp_f32_e32 v44, v44
	s_nop 0
	v_add_f32_e32 v44, 1.0, v44
	v_rcp_f32_e32 v44, v44
	s_nop 0
	v_mul_f32_e32 v42, v42, v44
	v_mul_f32_e32 v44, v42, v43
	v_mov_b32_e32 v42, v38
	v_mov_b32_e32 v43, v34
	v_pk_mul_f32 v[42:43], v[146:147], v[42:43] op_sel_hi:[0,1]
	v_mul_f32_e32 v34, 0xbfb8aa3b, v42
	v_exp_f32_e32 v34, v34
	s_nop 0
	v_add_f32_e32 v34, 1.0, v34
	v_rcp_f32_e32 v34, v34
	s_nop 0
	v_mul_f32_e32 v34, v42, v34
	v_mul_f32_e32 v42, v34, v43
	v_mov_b32_e32 v34, v39
	v_pk_mul_f32 v[34:35], v[146:147], v[34:35] op_sel_hi:[0,1]
	v_mul_f32_e32 v38, 0xbfb8aa3b, v34
	v_exp_f32_e32 v38, v38
	s_nop 0
	v_add_f32_e32 v38, 1.0, v38
	v_rcp_f32_e32 v38, v38
	s_nop 0
	v_mul_f32_e32 v34, v34, v38
	v_mul_f32_e32 v43, v34, v35
	v_mov_b32_e32 v34, v40
	v_mov_b32_e32 v35, v36
	v_pk_mul_f32 v[34:35], v[146:147], v[34:35] op_sel_hi:[0,1]
	v_mul_f32_e32 v36, 0xbfb8aa3b, v34
	v_exp_f32_e32 v36, v36
	v_lshl_add_u64 v[38:39], v[50:51], 0, v[114:115]
	v_add_f32_e32 v36, 1.0, v36
	v_rcp_f32_e32 v36, v36
	s_nop 0
	v_mul_f32_e32 v34, v34, v36
	v_mov_b32_e32 v36, v41
	v_mul_f32_e32 v40, v34, v35
	v_pk_mul_f32 v[34:35], v[146:147], v[36:37] op_sel_hi:[0,1]
	v_mul_f32_e32 v36, 0xbfb8aa3b, v34
	v_exp_f32_e32 v36, v36
	s_nop 0
	v_add_f32_e32 v36, 1.0, v36
	v_rcp_f32_e32 v36, v36
	s_nop 0
	v_mul_f32_e32 v34, v34, v36
	v_mul_f32_e32 v37, v34, v35
	v_cvt_pk_bf16_f32 v34, v46, v47
	v_cvt_pk_bf16_f32 v35, v48, v44
	v_cvt_pk_bf16_f32 v36, v42, v43
	v_cvt_pk_bf16_f32 v37, v40, v37
	global_store_dwordx4 v[38:39], v[34:37], off
	s_nop 1
	v_mov_b32_e32 v36, v30
	v_mov_b32_e32 v37, v26
	v_pk_mul_f32 v[36:37], v[144:145], v[36:37] op_sel_hi:[0,1]
	v_mul_f32_e32 v26, 0xbfb8aa3b, v36
	v_exp_f32_e32 v26, v26
	v_add_u32_e32 v34, 0xa0, v142
	v_mad_i64_i32 v[34:35], s[42:43], v34, s65, v[154:155]
	v_add_f32_e32 v26, 1.0, v26
	v_rcp_f32_e32 v26, v26
	s_nop 0
	v_mul_f32_e32 v26, v36, v26
	v_mul_f32_e32 v30, v26, v37
	v_mov_b32_e32 v26, v31
	v_pk_mul_f32 v[26:27], v[144:145], v[26:27] op_sel_hi:[0,1]
	v_mul_f32_e32 v31, 0xbfb8aa3b, v26
	v_exp_f32_e32 v31, v31
	s_nop 0
	v_add_f32_e32 v31, 1.0, v31
	v_rcp_f32_e32 v31, v31
	s_nop 0
	v_mul_f32_e32 v26, v26, v31
	v_mul_f32_e32 v31, v26, v27
	v_mov_b32_e32 v26, v32
	v_mov_b32_e32 v27, v28
	v_pk_mul_f32 v[26:27], v[144:145], v[26:27] op_sel_hi:[0,1]
	v_mul_f32_e32 v28, 0xbfb8aa3b, v26
	v_exp_f32_e32 v28, v28
	s_nop 0
	v_add_f32_e32 v28, 1.0, v28
	v_rcp_f32_e32 v28, v28
	s_nop 0
	v_mul_f32_e32 v26, v26, v28
	v_mov_b32_e32 v28, v33
	v_mul_f32_e32 v32, v26, v27
	v_pk_mul_f32 v[26:27], v[144:145], v[28:29] op_sel_hi:[0,1]
	v_mul_f32_e32 v28, 0xbfb8aa3b, v26
	v_exp_f32_e32 v28, v28
	s_nop 0
	v_add_f32_e32 v28, 1.0, v28
	v_rcp_f32_e32 v28, v28
	s_nop 0
	v_mul_f32_e32 v26, v26, v28
	v_mul_f32_e32 v28, v26, v27
; __device__ __forceinline__ unsigned cvt_pk_bf16(float lo, float hi) { unsigned r; asm volatile("v_cvt_pk_bf16_f32 %0, %1, %2" : "=v"(r) : "v"(lo), "v"(hi)); return r; }
; #define PG8_BAR __builtin_amdgcn_s_barrier()
;     __device__ __forceinline__ void operator()(const f32x4 (&acc)[2][2][4][2], const Unit& u, int wr, int wc, int fr, int fq, const float (&rsv)[8]) const {
;     ...
;             for (int m = 0; m < 4; ++m) { bf16_t* rowp = O + (size_t)(row0 + ai * HALF + m * 16) * ldc + col0; float r[8]; const float rr = rsv[ai * 4 + m];
; #pragma unroll
;                 for (int n = 0; n < 2; ++n)
; #pragma unroll
;                     for (int j = 0; j < 4; ++j) { const float g = acc[ai][0][m][n][j] * rr, up = acc[ai][1][m][n][j] * rr;
;                         const float e = __builtin_amdgcn_exp2f(g * -1.4426950408889634f); r[n * 4 + j] = g * __builtin_amdgcn_rcpf(1.0f + e) * up; }
;                 u32x4 w; w.x = cvt_pk_bf16(r[0], r[1]); w.y = cvt_pk_bf16(r[2], r[3]); w.z = cvt_pk_bf16(r[4], r[5]); w.w = cvt_pk_bf16(r[6], r[7]);
;                 *(u32x4*)rowp = w; }
; template <class Epi, class Sched, bool ALIGN_EPI = false, bool SP2 = false>
; __device__ __forceinline__ void gemm_phase(PG8_LAS unsigned char* lds, const Gemm g, const Sched& S, const Epi& E, const int tid_in) {
;     ...
;         if (!has_next) break;
; #pragma unroll
;         for (int a = 0; a < 2; ++a)
; #pragma unroll
;             for (int b = 0; b < 2; ++b)
; #pragma unroll
;                 for (int m = 0; m < 4; ++m)
; #pragma unroll
;                     for (int n = 0; n < 2; ++n) acc[a][b][m][n] = (f32x4){0.f, 0.f, 0.f, 0.f};
;         cur = nxt; cA = nA; cB = nB; ++ui;
;         if constexpr (ALIGN_EPI) { if (wr == 1) PG8_BAR; }
	v_mov_b32_e32 v26, v22
	v_mov_b32_e32 v27, v18
	v_pk_mul_f32 v[26:27], v[144:145], v[26:27] op_sel_hi:[0,1]
	v_mul_f32_e32 v18, 0xbfb8aa3b, v26
	v_exp_f32_e32 v18, v18
	s_nop 0
	v_add_f32_e32 v18, 1.0, v18
	v_rcp_f32_e32 v18, v18
	s_nop 0
	v_mul_f32_e32 v18, v26, v18
	v_mul_f32_e32 v26, v18, v27
	v_mov_b32_e32 v18, v23
	v_pk_mul_f32 v[18:19], v[144:145], v[18:19] op_sel_hi:[0,1]
	v_mul_f32_e32 v22, 0xbfb8aa3b, v18
	v_exp_f32_e32 v22, v22
	s_nop 0
	v_add_f32_e32 v22, 1.0, v22
	v_rcp_f32_e32 v22, v22
	s_nop 0
	v_mul_f32_e32 v18, v18, v22
	v_mul_f32_e32 v27, v18, v19
	v_mov_b32_e32 v18, v24
	v_mov_b32_e32 v19, v20
	v_pk_mul_f32 v[18:19], v[144:145], v[18:19] op_sel_hi:[0,1]
	v_mul_f32_e32 v20, 0xbfb8aa3b, v18
	v_exp_f32_e32 v20, v20
	v_lshl_add_u64 v[22:23], v[34:35], 0, v[114:115]
	v_add_f32_e32 v20, 1.0, v20
	v_rcp_f32_e32 v20, v20
	s_nop 0
	v_mul_f32_e32 v18, v18, v20
	v_mov_b32_e32 v20, v25
	v_mul_f32_e32 v24, v18, v19
	v_pk_mul_f32 v[18:19], v[144:145], v[20:21] op_sel_hi:[0,1]
	v_mul_f32_e32 v20, 0xbfb8aa3b, v18
	v_exp_f32_e32 v20, v20
	s_nop 0
	v_add_f32_e32 v20, 1.0, v20
	v_rcp_f32_e32 v20, v20
	s_nop 0
	v_mul_f32_e32 v18, v18, v20
	v_mul_f32_e32 v21, v18, v19
	v_cvt_pk_bf16_f32 v18, v30, v31
	v_cvt_pk_bf16_f32 v19, v32, v28
	v_cvt_pk_bf16_f32 v20, v26, v27
	v_cvt_pk_bf16_f32 v21, v24, v21
	global_store_dwordx4 v[22:23], v[18:21], off
	s_nop 1
	v_mov_b32_e32 v20, v14
	v_mov_b32_e32 v21, v10
	v_pk_mul_f32 v[20:21], v[140:141], v[20:21] op_sel_hi:[0,1]
	v_mul_f32_e32 v10, 0xbfb8aa3b, v20
	v_exp_f32_e32 v10, v10
	v_add_u32_e32 v18, 0xb0, v142
	v_mad_i64_i32 v[18:19], s[42:43], v18, s65, v[154:155]
	v_add_f32_e32 v10, 1.0, v10
	v_rcp_f32_e32 v10, v10
	s_nop 0
	v_mul_f32_e32 v10, v20, v10
	v_mul_f32_e32 v14, v10, v21
	v_mov_b32_e32 v10, v15
	v_pk_mul_f32 v[10:11], v[140:141], v[10:11] op_sel_hi:[0,1]
	v_mul_f32_e32 v15, 0xbfb8aa3b, v10
	v_exp_f32_e32 v15, v15
	s_nop 0
	v_add_f32_e32 v15, 1.0, v15
	v_rcp_f32_e32 v15, v15
	s_nop 0
	v_mul_f32_e32 v10, v10, v15
	v_mul_f32_e32 v15, v10, v11
	v_mov_b32_e32 v10, v16
	v_mov_b32_e32 v11, v12
	v_pk_mul_f32 v[10:11], v[140:141], v[10:11] op_sel_hi:[0,1]
	v_mul_f32_e32 v12, 0xbfb8aa3b, v10
	v_exp_f32_e32 v12, v12
	s_nop 0
	v_add_f32_e32 v12, 1.0, v12
	v_rcp_f32_e32 v12, v12
	s_nop 0
	v_mul_f32_e32 v10, v10, v12
	v_mov_b32_e32 v12, v17
	v_mul_f32_e32 v16, v10, v11
	v_pk_mul_f32 v[10:11], v[140:141], v[12:13] op_sel_hi:[0,1]
	v_mul_f32_e32 v12, 0xbfb8aa3b, v10
	v_exp_f32_e32 v12, v12
	s_nop 0
	v_add_f32_e32 v12, 1.0, v12
	v_rcp_f32_e32 v12, v12
	s_nop 0
	v_mul_f32_e32 v10, v10, v12
	v_mul_f32_e32 v12, v10, v11
	v_mov_b32_e32 v10, v6
	v_mov_b32_e32 v11, v2
	v_pk_mul_f32 v[10:11], v[140:141], v[10:11] op_sel_hi:[0,1]
	v_mul_f32_e32 v2, 0xbfb8aa3b, v10
	v_exp_f32_e32 v2, v2
	s_nop 0
	v_add_f32_e32 v2, 1.0, v2
	v_rcp_f32_e32 v2, v2
	s_nop 0
	v_mul_f32_e32 v2, v10, v2
	v_mul_f32_e32 v10, v2, v11
	v_mov_b32_e32 v2, v7
	v_pk_mul_f32 v[2:3], v[140:141], v[2:3] op_sel_hi:[0,1]
	v_mul_f32_e32 v6, 0xbfb8aa3b, v2
	v_exp_f32_e32 v6, v6
	s_nop 0
	v_add_f32_e32 v6, 1.0, v6
	v_rcp_f32_e32 v6, v6
	s_nop 0
	v_mul_f32_e32 v2, v2, v6
	v_mul_f32_e32 v11, v2, v3
	v_mov_b32_e32 v2, v8
	v_mov_b32_e32 v3, v4
	v_pk_mul_f32 v[2:3], v[140:141], v[2:3] op_sel_hi:[0,1]
	v_mul_f32_e32 v4, 0xbfb8aa3b, v2
	v_exp_f32_e32 v4, v4
	v_lshl_add_u64 v[6:7], v[18:19], 0, v[114:115]
	v_add_f32_e32 v4, 1.0, v4
	v_rcp_f32_e32 v4, v4
	s_nop 0
	v_mul_f32_e32 v2, v2, v4
	v_mov_b32_e32 v4, v9
	v_mul_f32_e32 v8, v2, v3
	v_pk_mul_f32 v[2:3], v[140:141], v[4:5] op_sel_hi:[0,1]
	v_mul_f32_e32 v4, 0xbfb8aa3b, v2
	v_exp_f32_e32 v4, v4
	s_nop 0
	v_add_f32_e32 v4, 1.0, v4
	v_rcp_f32_e32 v4, v4
	s_nop 0
	v_mul_f32_e32 v2, v2, v4
	v_mul_f32_e32 v5, v2, v3
	v_cvt_pk_bf16_f32 v2, v14, v15
	v_cvt_pk_bf16_f32 v3, v16, v12
	v_cvt_pk_bf16_f32 v4, v10, v11
	v_cvt_pk_bf16_f32 v5, v8, v5
	global_store_dwordx4 v[6:7], v[2:5], off
	s_cbranch_vccnz .LBB0_618
	s_andn2_b64 vcc, exec, s[10:11]
	s_cbranch_vccnz .LBB0_617
	s_barrier
	s_branch .LBB0_617

; #define PG8_STAGE(bufoff, gbase, voff) do { _Pragma("unroll") for (int _i = 0; _i < 2; ++_i) \
;         __builtin_amdgcn_global_load_lds((const unsigned*)((const char*)(gbase) + (voff)[_i]), (PG8_LAS unsigned*)(lds + (bufoff) + ldsw + _i * 8192), 16, 0, 0); } while (0)
; #define PG8_LDA(dst, b, h) do { _Pragma("unroll") for (int m = 0; m < 4; ++m) _Pragma("unroll") for (int k = 0; k < 2; ++k) dst[m][k] = *(const PG8_LAS bf16x8*)(lds + PG8_SA(b, h) + aoff + m * 2048 + k * 1024); } while (0)
; #define PG8_LDB(dst, b, h) do { _Pragma("unroll") for (int n = 0; n < 2; ++n) _Pragma("unroll") for (int k = 0; k < 2; ++k) dst[n][k] = *(const PG8_LAS bf16x8*)(lds + PG8_SB(b, h) + boff + n * 2048 + k * 1024); } while (0)
; #define PG8_SCHED __builtin_amdgcn_sched_barrier(0)
; template <class Epi, class Sched, bool ALIGN_EPI = false, bool SP2 = false>
; __device__ __forceinline__ void gemm_phase(PG8_LAS unsigned char* lds, const Gemm g, const Sched& S, const Epi& E, const int tid_in) {
;     ...
;         for (int t = 0; t < nt; t += 2) {
;             const bool last = (t == nt - 2);
;             const char* a1 = cA + (size_t)(t + 1) * kstep;
;             const char* a2 = last ? nA : cA + (size_t)(t + 2) * kstep; const char* b2 = last ? nB : cB + (size_t)(t + 2) * kstep;
;             const char* a3 = a2 + kstep; const char* b3 = b2 + kstep;
;             if (last && has_next) S.a_ready(nxt);
;             if constexpr (SP2) {
;             PG8_LDB(B0, 0, 0); PG8_LDB(B1, 0, 1); PG8_SCHED; PG8_LDA(At, 0, 0); PG8_STAGE(PG8_SA(1, 1), a1 + hstep, voffA);
;     ...
;         for (int a = 0; a < 2; ++a)
; #pragma unroll
;             for (int b = 0; b < 2; ++b)
; #pragma unroll
;                 for (int m = 0; m < 4; ++m)
; #pragma unroll
;                     for (int n = 0; n < 2; ++n) acc[a][b][m][n] = (f32x4){0.f, 0.f, 0.f, 0.f};
.LBB0_702:
	s_add_u32 s62, s20, 0x100
	v_mov_b32_e32 v2, 0
	s_addc_u32 s63, s21, 0
	s_mov_b32 s64, -2
	v_mov_b32_e32 v3, v2
	v_mov_b64_e32 v[4:5], 0
	v_mov_b64_e32 v[6:7], 0
	v_mov_b64_e32 v[8:9], 0
	v_mov_b64_e32 v[10:11], 0
	v_mov_b64_e32 v[12:13], 0
	v_mov_b64_e32 v[18:19], 0
	v_mov_b64_e32 v[20:21], 0
	v_mov_b64_e32 v[26:27], 0
	v_mov_b64_e32 v[28:29], 0
	v_mov_b64_e32 v[34:35], 0
	v_mov_b64_e32 v[36:37], 0
	v_mov_b64_e32 v[42:43], 0
	v_mov_b64_e32 v[44:45], 0
	v_mov_b64_e32 v[50:51], 0
	v_mov_b64_e32 v[52:53], 0
	v_mov_b64_e32 v[14:15], 0
	v_mov_b64_e32 v[16:17], 0
	v_mov_b64_e32 v[22:23], 0
	v_mov_b64_e32 v[24:25], 0
	v_mov_b64_e32 v[30:31], 0
	v_mov_b64_e32 v[32:33], 0
	v_mov_b64_e32 v[38:39], 0
	v_mov_b64_e32 v[40:41], 0
	v_mov_b64_e32 v[46:47], 0
	v_mov_b64_e32 v[48:49], 0
	v_mov_b64_e32 v[54:55], 0
	v_mov_b64_e32 v[56:57], 0
	v_mov_b64_e32 v[58:59], 0
	v_mov_b64_e32 v[60:61], 0
	v_mov_b64_e32 v[62:63], 0
	v_mov_b64_e32 v[64:65], 0
	v_mov_b64_e32 v[66:67], 0
	v_mov_b64_e32 v[68:69], 0
	v_mov_b64_e32 v[70:71], 0
	v_mov_b64_e32 v[72:73], 0
	v_mov_b64_e32 v[74:75], 0
	v_mov_b64_e32 v[76:77], 0
	v_mov_b64_e32 v[82:83], 0
	v_mov_b64_e32 v[84:85], 0
	v_mov_b64_e32 v[90:91], 0
	v_mov_b64_e32 v[92:93], 0
	v_mov_b64_e32 v[98:99], 0
	v_mov_b64_e32 v[100:101], 0
	v_mov_b64_e32 v[106:107], 0
	v_mov_b64_e32 v[108:109], 0
	v_mov_b64_e32 v[114:115], 0
	v_mov_b64_e32 v[116:117], 0
	v_mov_b64_e32 v[78:79], 0
	v_mov_b64_e32 v[80:81], 0
	v_mov_b64_e32 v[86:87], 0
	v_mov_b64_e32 v[88:89], 0
	v_mov_b64_e32 v[94:95], 0
	v_mov_b64_e32 v[96:97], 0
	v_mov_b64_e32 v[102:103], 0
	v_mov_b64_e32 v[104:105], 0
	v_mov_b64_e32 v[110:111], 0
	v_mov_b64_e32 v[112:113], 0
	v_mov_b64_e32 v[118:119], 0
	v_mov_b64_e32 v[120:121], 0
	v_mov_b64_e32 v[122:123], 0
	v_mov_b64_e32 v[124:125], 0
	v_mov_b64_e32 v[126:127], 0
	v_mov_b64_e32 v[128:129], 0
.LBB0_703:
	s_add_u32 s20, s18, 0x100
	s_addc_u32 s21, s19, 0
	s_add_i32 s70, 0, 0x10000
	s_cmp_eq_u32 s64, 40
	s_cselect_b32 s69, s5, s21
	s_cselect_b32 s68, s4, s20
	v_add_u32_e32 v140, s70, v143
	s_cselect_b32 s23, s17, s63
	s_cselect_b32 s22, s16, s62
	s_add_i32 s71, 0, 0x14000
	ds_read_b128 v[146:149], v140
	ds_read_b128 v[150:153], v140 offset:1024
	ds_read_b128 v[154:157], v140 offset:2048
	ds_read_b128 v[158:161], v140 offset:3072
	v_add_u32_e32 v140, s71, v143
	ds_read_b128 v[162:165], v140
	ds_read_b128 v[166:169], v140 offset:1024
	ds_read_b128 v[170:173], v140 offset:2048
	ds_read_b128 v[174:177], v140 offset:3072
	s_add_i32 m0, s34, 0xc000
	ds_read_b128 v[178:181], v145
	ds_read_b128 v[182:185], v145 offset:1024
	ds_read_b128 v[186:189], v145 offset:2048
	ds_read_b128 v[190:193], v145 offset:3072
	ds_read_b128 v[194:197], v145 offset:4096
	ds_read_b128 v[198:201], v145 offset:5120
	ds_read_b128 v[202:205], v145 offset:6144
	ds_read_b128 v[206:209], v145 offset:7168
	global_load_lds_dwordx4 v136, s[18:19]
	s_add_i32 m0, s34, 0xe000
	s_nop 0
	global_load_lds_dwordx4 v138, s[18:19]
	s_cmp_lg_u32 s64, -2
	s_cbranch_scc1 .Lra_n_d1
	s_cmp_lt_u32 s43, 2
	s_cbranch_scc1 .Lra_n_d1
	s_waitcnt vmcnt(24)
	s_branch .Lra_d_d1

; #define PG8_STAGE(bufoff, gbase, voff) do { _Pragma("unroll") for (int _i = 0; _i < 2; ++_i) \
;         __builtin_amdgcn_global_load_lds((const unsigned*)((const char*)(gbase) + (voff)[_i]), (PG8_LAS unsigned*)(lds + (bufoff) + ldsw + _i * 8192), 16, 0, 0); } while (0)
; #define PG8_LDA(dst, b, h) do { _Pragma("unroll") for (int m = 0; m < 4; ++m) _Pragma("unroll") for (int k = 0; k < 2; ++k) dst[m][k] = *(const PG8_LAS bf16x8*)(lds + PG8_SA(b, h) + aoff + m * 2048 + k * 1024); } while (0)
; #define PG8_MMA(ai, bj, At, Bt) do { __builtin_amdgcn_s_setprio(1); _Pragma("unroll") for (int m = 0; m < 4; ++m) _Pragma("unroll") for (int n = 0; n < 2; ++n) _Pragma("unroll") for (int k = 0; k < 2; ++k) \
;         acc[ai][bj][m][n] = __builtin_amdgcn_mfma_f32_16x16x32_bf16(Bt[n][k], At[m][k], acc[ai][bj][m][n], 0, 0, 0); __builtin_amdgcn_s_setprio(0); } while (0)
; #define PG8_WAIT_V(n) asm volatile("s_waitcnt vmcnt(" #n ")" ::: "memory")
; #define PG8_WAIT_L(n) asm volatile("s_waitcnt lgkmcnt(" #n ")" ::: "memory")
; #define PG8_BAR __builtin_amdgcn_s_barrier()
; #define PG8_SCHED __builtin_amdgcn_sched_barrier(0)
; template <class Epi, class Sched, bool ALIGN_EPI = false, bool SP2 = false>
; __device__ __forceinline__ void gemm_phase(PG8_LAS unsigned char* lds, const Gemm g, const Sched& S, const Epi& E, const int tid_in) {
;     ...
;             PG8_WAIT_V(8); PG8_WAIT_L(0); PG8_BAR; PG8_MMA(0, 0, At, B0); PG8_MMA(0, 1, At, B1); PG8_BAR; PG8_SCHED;
;             PG8_LDA(At, 0, 1); PG8_STAGE(PG8_SB(0, 0), b2, voffB); PG8_STAGE(PG8_SB(0, 1), b2 + hstep, voffB); PG8_STAGE(PG8_SA(0, 0), a2, voffA);
;             PG8_WAIT_V(8); PG8_WAIT_L(0); PG8_BAR; PG8_MMA(1, 0, At, B0); PG8_MMA(1, 1, At, B1); PG8_BAR; PG8_SCHED;
.Lra_d_d1:
	s_waitcnt lgkmcnt(0)
	s_barrier
	s_setprio 1
	s_waitcnt lgkmcnt(0)
	v_mfma_f32_16x16x32_bf16 v[126:129], v[146:149], v[178:181], v[126:129]
	v_mfma_f32_16x16x32_bf16 v[122:125], v[154:157], v[178:181], v[122:125]
	v_mfma_f32_16x16x32_bf16 v[118:121], v[146:149], v[186:189], v[118:121]
	v_mfma_f32_16x16x32_bf16 v[110:113], v[154:157], v[186:189], v[110:113]
	v_mfma_f32_16x16x32_bf16 v[102:105], v[146:149], v[194:197], v[102:105]
	v_mfma_f32_16x16x32_bf16 v[94:97], v[154:157], v[194:197], v[94:97]
	v_mfma_f32_16x16x32_bf16 v[86:89], v[146:149], v[202:205], v[86:89]
	v_mfma_f32_16x16x32_bf16 v[78:81], v[154:157], v[202:205], v[78:81]
	v_mfma_f32_16x16x32_bf16 v[126:129], v[150:153], v[182:185], v[126:129]
	v_mfma_f32_16x16x32_bf16 v[122:125], v[158:161], v[182:185], v[122:125]
	v_mfma_f32_16x16x32_bf16 v[118:121], v[150:153], v[190:193], v[118:121]
	v_mfma_f32_16x16x32_bf16 v[110:113], v[158:161], v[190:193], v[110:113]
	v_mfma_f32_16x16x32_bf16 v[102:105], v[150:153], v[198:201], v[102:105]
	v_mfma_f32_16x16x32_bf16 v[94:97], v[158:161], v[198:201], v[94:97]
	v_mfma_f32_16x16x32_bf16 v[86:89], v[150:153], v[206:209], v[86:89]
	v_mfma_f32_16x16x32_bf16 v[78:81], v[158:161], v[206:209], v[78:81]
	s_setprio 0
	s_setprio 1
	v_mfma_f32_16x16x32_bf16 v[114:117], v[162:165], v[178:181], v[114:117]
	v_mfma_f32_16x16x32_bf16 v[106:109], v[170:173], v[178:181], v[106:109]
	v_mfma_f32_16x16x32_bf16 v[98:101], v[162:165], v[186:189], v[98:101]
	v_mfma_f32_16x16x32_bf16 v[90:93], v[170:173], v[186:189], v[90:93]
	v_mfma_f32_16x16x32_bf16 v[82:85], v[162:165], v[194:197], v[82:85]
	v_mfma_f32_16x16x32_bf16 v[74:77], v[170:173], v[194:197], v[74:77]
	v_mfma_f32_16x16x32_bf16 v[70:73], v[162:165], v[202:205], v[70:73]
	v_mfma_f32_16x16x32_bf16 v[66:69], v[170:173], v[202:205], v[66:69]
	v_mfma_f32_16x16x32_bf16 v[114:117], v[166:169], v[182:185], v[114:117]
	v_mfma_f32_16x16x32_bf16 v[106:109], v[174:177], v[182:185], v[106:109]
	v_mfma_f32_16x16x32_bf16 v[98:101], v[166:169], v[190:193], v[98:101]
	v_mfma_f32_16x16x32_bf16 v[90:93], v[174:177], v[190:193], v[90:93]
	v_mfma_f32_16x16x32_bf16 v[82:85], v[166:169], v[198:201], v[82:85]
	v_mfma_f32_16x16x32_bf16 v[74:77], v[174:177], v[198:201], v[74:77]
	v_mfma_f32_16x16x32_bf16 v[70:73], v[166:169], v[206:209], v[70:73]
	v_mfma_f32_16x16x32_bf16 v[66:69], v[174:177], v[206:209], v[66:69]
	s_setprio 0
	s_barrier
	s_add_i32 s18, s70, s29
	s_mov_b32 m0, s18
	ds_read_b128 v[178:181], v145 offset:16384
	ds_read_b128 v[182:185], v145 offset:17408
	ds_read_b128 v[186:189], v145 offset:18432
	ds_read_b128 v[190:193], v145 offset:19456
	ds_read_b128 v[194:197], v145 offset:20480
	ds_read_b128 v[198:201], v145 offset:21504
	ds_read_b128 v[202:205], v145 offset:22528
	ds_read_b128 v[206:209], v145 offset:23552
	global_load_lds_dwordx4 v0, s[22:23]
	s_add_i32 m0, s18, 0x2000
	s_add_u32 s18, s22, 0xb0000
	s_addc_u32 s19, s23, 0
	s_add_i32 s70, s71, s29
	global_load_lds_dwordx4 v134, s[22:23]
	s_mov_b32 m0, s70
	s_nop 0
	global_load_lds_dwordx4 v0, s[18:19]
	s_add_i32 m0, s70, 0x2000
	s_nop 0
	global_load_lds_dwordx4 v134, s[18:19]
	s_mov_b32 m0, s34
	s_nop 0
	global_load_lds_dwordx4 v130, s[68:69]
	s_mov_b32 m0, s35
	s_nop 0
	global_load_lds_dwordx4 v132, s[68:69]
	s_cmp_lg_u32 s64, -2
	s_cbranch_scc1 .Lra_n_d2
	s_cmp_lt_u32 s43, 2
	s_cbranch_scc1 .Lra_n_d2
	s_waitcnt vmcnt(24)
	s_branch .Lra_d_d2

; #define PG8_STAGE(bufoff, gbase, voff) do { _Pragma("unroll") for (int _i = 0; _i < 2; ++_i) \
;         __builtin_amdgcn_global_load_lds((const unsigned*)((const char*)(gbase) + (voff)[_i]), (PG8_LAS unsigned*)(lds + (bufoff) + ldsw + _i * 8192), 16, 0, 0); } while (0)
; #define PG8_LDA(dst, b, h) do { _Pragma("unroll") for (int m = 0; m < 4; ++m) _Pragma("unroll") for (int k = 0; k < 2; ++k) dst[m][k] = *(const PG8_LAS bf16x8*)(lds + PG8_SA(b, h) + aoff + m * 2048 + k * 1024); } while (0)
; #define PG8_LDB(dst, b, h) do { _Pragma("unroll") for (int n = 0; n < 2; ++n) _Pragma("unroll") for (int k = 0; k < 2; ++k) dst[n][k] = *(const PG8_LAS bf16x8*)(lds + PG8_SB(b, h) + boff + n * 2048 + k * 1024); } while (0)
; #define PG8_MMA(ai, bj, At, Bt) do { __builtin_amdgcn_s_setprio(1); _Pragma("unroll") for (int m = 0; m < 4; ++m) _Pragma("unroll") for (int n = 0; n < 2; ++n) _Pragma("unroll") for (int k = 0; k < 2; ++k) \
;         acc[ai][bj][m][n] = __builtin_amdgcn_mfma_f32_16x16x32_bf16(Bt[n][k], At[m][k], acc[ai][bj][m][n], 0, 0, 0); __builtin_amdgcn_s_setprio(0); } while (0)
; #define PG8_WAIT_V(n) asm volatile("s_waitcnt vmcnt(" #n ")" ::: "memory")
; #define PG8_WAIT_L(n) asm volatile("s_waitcnt lgkmcnt(" #n ")" ::: "memory")
; #define PG8_BAR __builtin_amdgcn_s_barrier()
; #define PG8_SCHED __builtin_amdgcn_sched_barrier(0)
; template <class Epi, class Sched, bool ALIGN_EPI = false, bool SP2 = false>
; __device__ __forceinline__ void gemm_phase(PG8_LAS unsigned char* lds, const Gemm g, const Sched& S, const Epi& E, const int tid_in) {
;     ...
;             PG8_WAIT_V(8); PG8_WAIT_L(0); PG8_BAR; PG8_MMA(1, 0, At, B0); PG8_MMA(1, 1, At, B1); PG8_BAR; PG8_SCHED;
;             PG8_LDB(B0, 1, 0); PG8_LDB(B1, 1, 1); PG8_SCHED; PG8_LDA(At, 1, 0); PG8_STAGE(PG8_SA(0, 1), a2 + hstep, voffA);
;             PG8_WAIT_V(8); PG8_WAIT_L(0); PG8_BAR; PG8_MMA(0, 0, At, B0); PG8_MMA(0, 1, At, B1); PG8_BAR; PG8_SCHED;
.Lra_d_d2:
	s_waitcnt lgkmcnt(0)
	s_barrier
	s_setprio 1
	s_waitcnt lgkmcnt(0)
	v_mfma_f32_16x16x32_bf16 v[62:65], v[146:149], v[178:181], v[62:65]
	v_mfma_f32_16x16x32_bf16 v[58:61], v[154:157], v[178:181], v[58:61]
	v_mfma_f32_16x16x32_bf16 v[54:57], v[146:149], v[186:189], v[54:57]
	v_mfma_f32_16x16x32_bf16 v[46:49], v[154:157], v[186:189], v[46:49]
	v_mfma_f32_16x16x32_bf16 v[38:41], v[146:149], v[194:197], v[38:41]
	v_mfma_f32_16x16x32_bf16 v[30:33], v[154:157], v[194:197], v[30:33]
	v_mfma_f32_16x16x32_bf16 v[22:25], v[146:149], v[202:205], v[22:25]
	v_mfma_f32_16x16x32_bf16 v[14:17], v[154:157], v[202:205], v[14:17]
	v_mfma_f32_16x16x32_bf16 v[62:65], v[150:153], v[182:185], v[62:65]
	v_mfma_f32_16x16x32_bf16 v[58:61], v[158:161], v[182:185], v[58:61]
	v_mfma_f32_16x16x32_bf16 v[54:57], v[150:153], v[190:193], v[54:57]
	v_mfma_f32_16x16x32_bf16 v[46:49], v[158:161], v[190:193], v[46:49]
	v_mfma_f32_16x16x32_bf16 v[38:41], v[150:153], v[198:201], v[38:41]
	v_mfma_f32_16x16x32_bf16 v[30:33], v[158:161], v[198:201], v[30:33]
	v_mfma_f32_16x16x32_bf16 v[22:25], v[150:153], v[206:209], v[22:25]
	v_mfma_f32_16x16x32_bf16 v[14:17], v[158:161], v[206:209], v[14:17]
	s_setprio 0
	s_setprio 1
	v_mfma_f32_16x16x32_bf16 v[50:53], v[162:165], v[178:181], v[50:53]
	v_mfma_f32_16x16x32_bf16 v[42:45], v[170:173], v[178:181], v[42:45]
	v_mfma_f32_16x16x32_bf16 v[34:37], v[162:165], v[186:189], v[34:37]
	v_mfma_f32_16x16x32_bf16 v[26:29], v[170:173], v[186:189], v[26:29]
	v_mfma_f32_16x16x32_bf16 v[18:21], v[162:165], v[194:197], v[18:21]
	v_mfma_f32_16x16x32_bf16 v[10:13], v[170:173], v[194:197], v[10:13]
	v_mfma_f32_16x16x32_bf16 v[6:9], v[162:165], v[202:205], v[6:9]
	v_mfma_f32_16x16x32_bf16 v[2:5], v[170:173], v[202:205], v[2:5]
	v_mfma_f32_16x16x32_bf16 v[50:53], v[166:169], v[182:185], v[50:53]
	v_mfma_f32_16x16x32_bf16 v[42:45], v[174:177], v[182:185], v[42:45]
	v_mfma_f32_16x16x32_bf16 v[34:37], v[166:169], v[190:193], v[34:37]
	v_mfma_f32_16x16x32_bf16 v[26:29], v[174:177], v[190:193], v[26:29]
	v_mfma_f32_16x16x32_bf16 v[18:21], v[166:169], v[198:201], v[18:21]
	v_mfma_f32_16x16x32_bf16 v[10:13], v[174:177], v[198:201], v[10:13]
	v_mfma_f32_16x16x32_bf16 v[6:9], v[166:169], v[206:209], v[6:9]
	v_mfma_f32_16x16x32_bf16 v[2:5], v[174:177], v[206:209], v[2:5]
	s_setprio 0
	s_barrier
	s_add_i32 s70, 0, 0x18000
	s_add_i32 s71, 0, 0x1c000
	v_add_u32_e32 v158, s70, v143
	v_add_u32_e32 v174, s71, v143
	ds_read_b128 v[146:149], v158
	ds_read_b128 v[150:153], v158 offset:1024
	ds_read_b128 v[154:157], v158 offset:2048
	ds_read_b128 v[158:161], v158 offset:3072
	ds_read_b128 v[162:165], v174
	ds_read_b128 v[166:169], v174 offset:1024
	ds_read_b128 v[170:173], v174 offset:2048
	ds_read_b128 v[174:177], v174 offset:3072
	s_add_u32 s18, s68, 0xb0000
	s_addc_u32 s19, s69, 0
	s_mov_b32 m0, s36
	ds_read_b128 v[178:181], v145 offset:32768
	ds_read_b128 v[182:185], v145 offset:33792
	ds_read_b128 v[186:189], v145 offset:34816
	ds_read_b128 v[190:193], v145 offset:35840
	ds_read_b128 v[194:197], v145 offset:36864
	ds_read_b128 v[198:201], v145 offset:37888
	ds_read_b128 v[202:205], v145 offset:38912
	ds_read_b128 v[206:209], v145 offset:39936
	global_load_lds_dwordx4 v130, s[18:19]
	s_mov_b32 m0, s37
	s_nop 0
	global_load_lds_dwordx4 v132, s[18:19]
	s_waitcnt vmcnt(8)
	s_waitcnt lgkmcnt(0)
	s_barrier
	s_setprio 1
	s_waitcnt lgkmcnt(0)
	v_mfma_f32_16x16x32_bf16 v[126:129], v[146:149], v[178:181], v[126:129]
	v_mfma_f32_16x16x32_bf16 v[122:125], v[154:157], v[178:181], v[122:125]
	v_mfma_f32_16x16x32_bf16 v[118:121], v[146:149], v[186:189], v[118:121]
	v_mfma_f32_16x16x32_bf16 v[110:113], v[154:157], v[186:189], v[110:113]
	v_mfma_f32_16x16x32_bf16 v[102:105], v[146:149], v[194:197], v[102:105]
	v_mfma_f32_16x16x32_bf16 v[94:97], v[154:157], v[194:197], v[94:97]
	v_mfma_f32_16x16x32_bf16 v[86:89], v[146:149], v[202:205], v[86:89]
	v_mfma_f32_16x16x32_bf16 v[78:81], v[154:157], v[202:205], v[78:81]
	v_mfma_f32_16x16x32_bf16 v[126:129], v[150:153], v[182:185], v[126:129]
	v_mfma_f32_16x16x32_bf16 v[122:125], v[158:161], v[182:185], v[122:125]
	v_mfma_f32_16x16x32_bf16 v[118:121], v[150:153], v[190:193], v[118:121]
	v_mfma_f32_16x16x32_bf16 v[110:113], v[158:161], v[190:193], v[110:113]
	v_mfma_f32_16x16x32_bf16 v[102:105], v[150:153], v[198:201], v[102:105]
	v_mfma_f32_16x16x32_bf16 v[94:97], v[158:161], v[198:201], v[94:97]
	v_mfma_f32_16x16x32_bf16 v[86:89], v[150:153], v[206:209], v[86:89]
	v_mfma_f32_16x16x32_bf16 v[78:81], v[158:161], v[206:209], v[78:81]
	s_setprio 0
	s_setprio 1
	v_mfma_f32_16x16x32_bf16 v[114:117], v[162:165], v[178:181], v[114:117]
	v_mfma_f32_16x16x32_bf16 v[106:109], v[170:173], v[178:181], v[106:109]
	v_mfma_f32_16x16x32_bf16 v[98:101], v[162:165], v[186:189], v[98:101]
	v_mfma_f32_16x16x32_bf16 v[90:93], v[170:173], v[186:189], v[90:93]
	v_mfma_f32_16x16x32_bf16 v[82:85], v[162:165], v[194:197], v[82:85]
	v_mfma_f32_16x16x32_bf16 v[74:77], v[170:173], v[194:197], v[74:77]
	v_mfma_f32_16x16x32_bf16 v[70:73], v[162:165], v[202:205], v[70:73]
	v_mfma_f32_16x16x32_bf16 v[66:69], v[170:173], v[202:205], v[66:69]
	v_mfma_f32_16x16x32_bf16 v[114:117], v[166:169], v[182:185], v[114:117]
	v_mfma_f32_16x16x32_bf16 v[106:109], v[174:177], v[182:185], v[106:109]
	v_mfma_f32_16x16x32_bf16 v[98:101], v[166:169], v[190:193], v[98:101]
	v_mfma_f32_16x16x32_bf16 v[90:93], v[174:177], v[190:193], v[90:93]
	v_mfma_f32_16x16x32_bf16 v[82:85], v[166:169], v[198:201], v[82:85]
	v_mfma_f32_16x16x32_bf16 v[74:77], v[174:177], v[198:201], v[74:77]
	v_mfma_f32_16x16x32_bf16 v[70:73], v[166:169], v[206:209], v[70:73]
	v_mfma_f32_16x16x32_bf16 v[66:69], v[174:177], v[206:209], v[66:69]
	s_setprio 0
	s_barrier
; #define PG8_STAGE(bufoff, gbase, voff) do { _Pragma("unroll") for (int _i = 0; _i < 2; ++_i) \
;         __builtin_amdgcn_global_load_lds((const unsigned*)((const char*)(gbase) + (voff)[_i]), (PG8_LAS unsigned*)(lds + (bufoff) + ldsw + _i * 8192), 16, 0, 0); } while (0)
; #define PG8_WAIT_V(n) asm volatile("s_waitcnt vmcnt(" #n ")" ::: "memory")
; #define PG8_WAIT_L(n) asm volatile("s_waitcnt lgkmcnt(" #n ")" ::: "memory")
; template <class Epi, class Sched, bool ALIGN_EPI = false, bool SP2 = false>
; __device__ __forceinline__ void gemm_phase(PG8_LAS unsigned char* lds, const Gemm g, const Sched& S, const Epi& E, const int tid_in) {
;     ...
;             PG8_LDA(At, 1, 1); PG8_STAGE(PG8_SB(1, 0), b3, voffB); PG8_STAGE(PG8_SB(1, 1), b3 + hstep, voffB); PG8_STAGE(PG8_SA(1, 0), a3, voffA);
;             PG8_WAIT_V(8); PG8_WAIT_L(0); PG8_BAR; PG8_MMA(1, 0, At, B0); PG8_MMA(1, 1, At, B1); PG8_BAR; PG8_SCHED;
;             } else {
;             PG8_LDB(B0, 0, 0); PG8_SCHED; PG8_LDA(At, 0, 0); PG8_STAGE(PG8_SA(1, 1), a1 + hstep, voffA);
;             PG8_WAIT_L(8); PG8_BAR; PG8_WAIT_L(0); PG8_MMA(0, 0, At, B0); PG8_BAR; PG8_SCHED;
;             PG8_LDB(B1, 0, 1); PG8_STAGE(PG8_SB(0, 0), b2, voffB);
;             PG8_BAR; PG8_WAIT_L(0); PG8_MMA(0, 1, At, B1); PG8_BAR;
;             PG8_LDA(At, 0, 1); PG8_STAGE(PG8_SA(0, 0), a2, voffA);
;             PG8_BAR; PG8_WAIT_L(0); PG8_MMA(1, 0, At, B0); PG8_BAR; PG8_SCHED;
;             PG8_STAGE(PG8_SB(0, 1), b2 + hstep, voffB);
;             PG8_WAIT_V(6); PG8_BAR; PG8_MMA(1, 1, At, B1); PG8_BAR;
;             PG8_LDB(B0, 1, 0); PG8_SCHED; PG8_LDA(At, 1, 0); PG8_STAGE(PG8_SA(0, 1), a2 + hstep, voffA);
;             PG8_WAIT_L(8); PG8_BAR; PG8_WAIT_L(0); PG8_MMA(0, 0, At, B0); PG8_BAR; PG8_SCHED;
;             PG8_LDB(B1, 1, 1); PG8_STAGE(PG8_SB(1, 0), b3, voffB);
;             PG8_BAR; PG8_WAIT_L(0); PG8_MMA(0, 1, At, B1); PG8_BAR;
;             PG8_LDA(At, 1, 1); PG8_STAGE(PG8_SA(1, 0), a3, voffA);
;             PG8_BAR; PG8_WAIT_L(0); PG8_MMA(1, 0, At, B0); PG8_BAR; PG8_SCHED;
;             PG8_STAGE(PG8_SB(1, 1), b3 + hstep, voffB);
;             PG8_WAIT_V(6); PG8_BAR; PG8_MMA(1, 1, At, B1); PG8_BAR;
;             }
;         }
;         if constexpr (ALIGN_EPI) { if (wr == 0) PG8_BAR; }
;         if constexpr (!Epi::AFTER_DRAIN) { E(acc, cur, wr, wc, fr, fq, rsv); S.done(cur); }
	s_add_i32 s18, s70, s29
	s_mov_b32 m0, s18
	ds_read_b128 v[178:181], v145 offset:49152
	ds_read_b128 v[182:185], v145 offset:50176
	ds_read_b128 v[186:189], v145 offset:51200
	ds_read_b128 v[190:193], v145 offset:52224
	ds_read_b128 v[194:197], v145 offset:53248
	ds_read_b128 v[198:201], v145 offset:54272
	ds_read_b128 v[202:205], v145 offset:55296
	ds_read_b128 v[206:209], v145 offset:56320
	s_add_u32 s44, s22, 0x80
	s_addc_u32 s45, s23, 0
	global_load_lds_dwordx4 v0, s[44:45]
	s_add_i32 m0, s18, 0x2000
	s_add_u32 s18, s22, 0xb0080
	s_addc_u32 s19, s23, 0
	s_add_i32 s22, s71, s29
	global_load_lds_dwordx4 v134, s[44:45]
	s_mov_b32 m0, s22
	s_nop 0
	global_load_lds_dwordx4 v0, s[18:19]
	s_add_i32 m0, s22, 0x2000
	s_nop 0
	global_load_lds_dwordx4 v134, s[18:19]
	s_mov_b32 m0, s38
	s_nop 0
	s_add_u32 s44, s68, 0x80
	s_addc_u32 s45, s69, 0
	global_load_lds_dwordx4 v130, s[44:45]
	s_mov_b32 m0, s42
	s_nop 0
	global_load_lds_dwordx4 v132, s[44:45]
	s_waitcnt vmcnt(8)
	s_waitcnt lgkmcnt(0)
	s_barrier
	s_setprio 1
	s_waitcnt lgkmcnt(0)
	v_mfma_f32_16x16x32_bf16 v[62:65], v[146:149], v[178:181], v[62:65]
	v_mfma_f32_16x16x32_bf16 v[58:61], v[154:157], v[178:181], v[58:61]
	v_mfma_f32_16x16x32_bf16 v[54:57], v[146:149], v[186:189], v[54:57]
	v_mfma_f32_16x16x32_bf16 v[46:49], v[154:157], v[186:189], v[46:49]
	v_mfma_f32_16x16x32_bf16 v[38:41], v[146:149], v[194:197], v[38:41]
	v_mfma_f32_16x16x32_bf16 v[30:33], v[154:157], v[194:197], v[30:33]
	v_mfma_f32_16x16x32_bf16 v[22:25], v[146:149], v[202:205], v[22:25]
	v_mfma_f32_16x16x32_bf16 v[14:17], v[154:157], v[202:205], v[14:17]
	v_mfma_f32_16x16x32_bf16 v[62:65], v[150:153], v[182:185], v[62:65]
	v_mfma_f32_16x16x32_bf16 v[58:61], v[158:161], v[182:185], v[58:61]
	v_mfma_f32_16x16x32_bf16 v[54:57], v[150:153], v[190:193], v[54:57]
	v_mfma_f32_16x16x32_bf16 v[46:49], v[158:161], v[190:193], v[46:49]
	v_mfma_f32_16x16x32_bf16 v[38:41], v[150:153], v[198:201], v[38:41]
	v_mfma_f32_16x16x32_bf16 v[30:33], v[158:161], v[198:201], v[30:33]
	v_mfma_f32_16x16x32_bf16 v[22:25], v[150:153], v[206:209], v[22:25]
	v_mfma_f32_16x16x32_bf16 v[14:17], v[158:161], v[206:209], v[14:17]
	s_setprio 0
	s_setprio 1
	v_mfma_f32_16x16x32_bf16 v[50:53], v[162:165], v[178:181], v[50:53]
	v_mfma_f32_16x16x32_bf16 v[42:45], v[170:173], v[178:181], v[42:45]
	v_mfma_f32_16x16x32_bf16 v[34:37], v[162:165], v[186:189], v[34:37]
	v_mfma_f32_16x16x32_bf16 v[26:29], v[170:173], v[186:189], v[26:29]
	v_mfma_f32_16x16x32_bf16 v[18:21], v[162:165], v[194:197], v[18:21]
	v_mfma_f32_16x16x32_bf16 v[10:13], v[170:173], v[194:197], v[10:13]
	v_mfma_f32_16x16x32_bf16 v[6:9], v[162:165], v[202:205], v[6:9]
	v_mfma_f32_16x16x32_bf16 v[2:5], v[170:173], v[202:205], v[2:5]
	v_mfma_f32_16x16x32_bf16 v[50:53], v[166:169], v[182:185], v[50:53]
	v_mfma_f32_16x16x32_bf16 v[42:45], v[174:177], v[182:185], v[42:45]
	v_mfma_f32_16x16x32_bf16 v[34:37], v[166:169], v[190:193], v[34:37]
	v_mfma_f32_16x16x32_bf16 v[26:29], v[174:177], v[190:193], v[26:29]
	v_mfma_f32_16x16x32_bf16 v[18:21], v[166:169], v[198:201], v[18:21]
	v_mfma_f32_16x16x32_bf16 v[10:13], v[174:177], v[198:201], v[10:13]
	v_mfma_f32_16x16x32_bf16 v[6:9], v[166:169], v[206:209], v[6:9]
	v_mfma_f32_16x16x32_bf16 v[2:5], v[174:177], v[206:209], v[2:5]
	s_setprio 0
	s_barrier
	s_add_i32 s64, s64, 2
	s_add_u32 s62, s62, 0x100
	s_addc_u32 s63, s63, 0
	s_cmp_gt_u32 s64, 41
	s_mov_b64 s[18:19], s[20:21]
	s_cbranch_scc0 .LBB0_703
	s_mov_b64 s[44:45], 0x80
	s_and_b64 vcc, exec, s[14:15]
	s_cbranch_vccz .LBB0_706
	s_barrier
